# seams 2/7/11/15: cross-XCD arrival posted at the seam, generation checked once after the next GEMM's first K-loop (before its first store) instead of a blocking rendezvous
# speedup vs baseline: 1.0568x; 1.0134x over previous
; __device__ __forceinline__ unsigned xb_ld(unsigned* p)              { return __hip_atomic_load(p, __ATOMIC_RELAXED, __HIP_MEMORY_SCOPE_AGENT); }
; __device__ __forceinline__ unsigned xb_add(unsigned* p, unsigned v) { return __hip_atomic_fetch_add(p, v, __ATOMIC_RELAXED, __HIP_MEMORY_SCOPE_AGENT); }
; #define XB_SPIN(cond, bar) do { unsigned _sp = 0; while (cond) { __builtin_amdgcn_s_sleep(1); \
;     if ((++_sp & 255u) == 0u) { if (xb_ld(&(bar)[XB_TMO])) break; if (_sp > XB_SPIN_CAP) { atomicAdd(&(bar)[XB_TMO], 1u); break; } } } } while (0)
; __device__ __forceinline__ void xcd_barrier(const XcdBarrier& b) {
;     ...
;             const unsigned og = xb_add(&bar[XB_TOP], 1u);
;             const unsigned tg = og / nx;
;             if (og + 1u == (tg + 1u) * nx) xb_add(&bar[XB_TOPGEN], 1u);
;             else XB_SPIN(xb_ld(&bar[XB_TOPGEN]) == tg, bar);
;             __builtin_amdgcn_fence(__ATOMIC_ACQUIRE, "agent");
.LBB0_368:
	s_or_b64 exec, exec, s[10:11]
	v_cvt_f32_u32_e32 v3, v0
	s_waitcnt vmcnt(0)
	v_readfirstlane_b32 s3, v2
	s_add_u32 s10, s28, 0x183500
	s_addc_u32 s11, s29, 0
	v_rcp_iflag_f32_e32 v3, v3
	v_add_u32_e32 v1, s3, v1
	v_add_u32_e32 v4, 1, v1
	s_mov_b64 s[12:13], -1
	v_mul_f32_e32 v2, 0x4f7ffffe, v3
	v_cvt_u32_f32_e32 v2, v2
	v_sub_u32_e32 v3, 0, v0
	v_mul_lo_u32 v3, v3, v2
	v_mul_hi_u32 v3, v2, v3
	v_add_u32_e32 v2, v2, v3
	v_mul_hi_u32 v2, v1, v2
	v_mul_lo_u32 v3, v2, v0
	v_sub_u32_e32 v1, v1, v3
	v_add_u32_e32 v5, 1, v2
	v_cmp_ge_u32_e32 vcc, v1, v0
	v_sub_u32_e32 v3, v1, v0
	s_nop 0
	v_cndmask_b32_e32 v2, v2, v5, vcc
	v_cndmask_b32_e32 v1, v1, v3, vcc
	v_add_u32_e32 v3, 1, v2
	v_cmp_ge_u32_e32 vcc, v1, v0
	s_nop 1
	v_cndmask_b32_e32 v2, v2, v3, vcc
	v_mul_lo_u32 v1, v0, v2
	v_add_u32_e32 v0, v1, v0
	v_cmp_ne_u32_e32 vcc, v4, v0
	v_mov_b64_e32 v[0:1], s[10:11]
	v_readlane_b32 s101, v249, 48
	s_nop 3
	s_cmp_lg_u32 s101, 0
	s_cbranch_scc0 .Lnodefer_0
	s_andn2_b64 s[12:13], exec, vcc
	s_mov_b64 s[8:9], exec
	s_branch .LBB0_380
.Lnodefer_0:
	s_and_saveexec_b64 s[8:9], vcc
	s_cbranch_execz .LBB0_380
	v_mov_b32_e32 v0, 0
	global_load_dword v1, v0, s[10:11] sc1
	s_mov_b64 s[16:17], 0
	s_waitcnt vmcnt(0)
	v_cmp_eq_u32_e32 vcc, v1, v2
	s_and_saveexec_b64 s[14:15], vcc
	s_cbranch_execz .LBB0_379
	s_add_u32 s12, s28, 0x180200
	s_addc_u32 s13, s29, 0
	s_mov_b32 s3, 1
	s_branch .LBB0_372

; #define PG8_STAGE(bufoff, gbase, voff) do { _Pragma("unroll") for (int _i = 0; _i < 2; ++_i) \
;         __builtin_amdgcn_global_load_lds((const unsigned*)((const char*)(gbase) + (voff)[_i]), (PG8_LAS unsigned*)(lds + (bufoff) + ldsw + _i * 8192), 16, 0, 0); } while (0)
; template <class Epi, class Sched, bool ALIGN_EPI = false, bool SP2 = false>
; __device__ __forceinline__ void gemm_phase(PG8_LAS unsigned char* lds, const Gemm g, const Sched& S, const Epi& E) {
;     ...
;     if (!S.next(0, cur)) return;
;     f32x4 acc[2][2][4][2];
; #pragma unroll
;     for (int a = 0; a < 2; ++a)
; #pragma unroll
;         for (int b = 0; b < 2; ++b)
; #pragma unroll
;             for (int m = 0; m < 4; ++m)
; #pragma unroll
;                 for (int n = 0; n < 2; ++n) acc[a][b][m][n] = (f32x4){0.f, 0.f, 0.f, 0.f};
;     bf16x8 At[4][2], B0[2][2], B1[2][2];
;     const char* cA = (const char*)g.A + (size_t)cur.pm * tstep; const char* cB = (const char*)g.Bt + (size_t)cur.pn * tstep;
;     S.a_ready(cur);
;     if constexpr (SP2) {
;         PG8_STAGE(PG8_SB(0, 0), cB, voffB); PG8_STAGE(PG8_SB(0, 1), cB + hstep, voffB); PG8_STAGE(PG8_SA(0, 0), cA, voffA); PG8_STAGE(PG8_SA(0, 1), cA + hstep, voffA);
; __global__ void __launch_bounds__(NTHREADS, 2) mega_fwd(Args a) {
;     ...
;     if (IN(3)) { BUILD_RTAB(RT, T, 1536, false, 1) EpiWin E{VC, US, RT}; run_gemm(lds, XB, (const bf16_t*)(ws + WS_WIN), T, 1536, D, E); }
.LBB0_386:
	v_readlane_b32 s101, v249, 48
	s_nop 3
	s_cmp_lg_u32 s101, 0
	s_cselect_b32 s101, 2, 0
	v_writelane_b32 v249, s101, 49
	s_cmp_lt_i32 s30, 4
	s_cselect_b64 s[4:5], -1, 0
	s_add_u32 s46, s28, 0xc800000
	s_addc_u32 s47, s29, 0
	s_and_b64 s[6:7], s[4:5], s[0:1]
	s_andn2_b64 vcc, exec, s[6:7]
	s_cbranch_vccnz .LBB0_425
	s_ashr_i32 s3, s2, 31
	s_cmpk_lt_i32 s2, 0x300
	s_cbranch_scc0 .Lpro_skip_1
	v_readfirstlane_b32 s5, v197
	s_nop 3
	v_lshrrev_b32_e32 v0, 5, v197
	v_lshrrev_b32_e32 v2, 1, v197
	v_and_b32_e32 v0, 4, v0
	v_bfe_u32 v1, v197, 2, 2
	v_and_b32_e32 v11, 24, v2
	v_or3_b32 v0, v0, v1, v11
	v_lshlrev_b32_e32 v1, 4, v197
	v_add_u32_e32 v8, 0x2000, v1
	v_lshrrev_b32_e32 v2, 7, v8
	s_movk_i32 s0, 0xe0
	v_and_b32_e32 v4, 32, v197
	v_and_or_b32 v3, v2, s0, v0
	v_bitop3_b32 v9, v1, v4, 48 bitop3:0x6c
	v_and_b32_e32 v10, 64, v197
	v_bfe_u32 v12, v197, 2, 4
	s_movk_i32 s0, 0xf0
	v_or_b32_e32 v1, v9, v10
	v_and_or_b32 v2, v2, s0, v12
	v_lshl_or_b32 v130, v2, 11, v1
	v_lshrrev_b32_e32 v2, 3, v197
	s_movk_i32 s0, 0x60
	s_add_u32 s61, s28, 0x4a00000
	v_and_or_b32 v0, v2, s0, v0
	s_movk_i32 s0, 0x70
	s_addc_u32 s62, s29, 0
	v_lshl_or_b32 v132, v0, 11, v1
	v_and_or_b32 v0, v2, s0, v12
	s_lshr_b32 s0, s3, 29
	s_add_i32 s0, s2, s0
	s_lshr_b32 s8, s5, 6
	s_ashr_i32 s1, s0, 3
	s_and_b32 s0, s0, -8
	s_lshr_b32 s12, s5, 8
	s_lshl_b32 s63, s8, 10
	s_sub_i32 s0, s2, s0
	s_cmp_lt_i32 s0, 0
	s_movk_i32 s64, 0x61
	s_cselect_b32 s4, s64, 0x60
	s_mul_i32 s0, s4, s0
	s_add_i32 s0, s0, s1
	s_mul_hi_i32 s1, s0, 0x2aaaaaab
	s_lshr_b32 s4, s1, 31
	s_ashr_i32 s1, s1, 3
	s_add_i32 s1, s1, s4
	s_lshl_b32 s9, s1, 3
	s_mul_i32 s1, s1, 48
	s_sub_i32 s0, s0, s1
	s_bfe_i32 s1, s0, 0x80000
	s_bfe_u32 s1, s1, 0x3000c
	s_add_i32 s1, s0, s1
	s_bfe_i32 s4, s1, 0x80000
	s_and_b32 s1, s1, 0xf8
	s_sub_i32 s0, s0, s1
	s_sext_i32_i16 s4, s4
	s_sext_i32_i8 s0, s0
	s_lshr_b32 s4, s4, 3
	s_add_i32 s34, s9, s0
	s_ashr_i32 s35, s34, 31
	s_bfe_i64 s[10:11], s[4:5], 0x100000
	s_lshl_b64 s[0:1], s[34:35], 19
	s_lshl_b64 s[10:11], s[10:11], 19
	s_add_u32 s52, s61, s10
	s_addc_u32 s53, s62, s11
	s_add_i32 s35, s63, 0
	s_add_i32 m0, s35, 0x10000
	v_lshl_or_b32 v128, v3, 11, v1
	global_load_lds_dwordx4 v132, s[52:53]
	s_add_i32 m0, s35, 0x12000
	s_add_u32 s10, s52, 0x40000
	global_load_lds_dwordx4 v128, s[52:53]
	s_addc_u32 s11, s53, 0
	s_add_i32 m0, s35, 0x14000
	v_lshl_or_b32 v134, v0, 11, v1
	global_load_lds_dwordx4 v132, s[10:11]
	s_add_i32 m0, s35, 0x16000
	s_add_u32 s20, s36, s0
	s_addc_u32 s21, s37, s1
	s_add_i32 s65, s35, 0x2000
	global_load_lds_dwordx4 v128, s[10:11]
	s_mov_b32 m0, s35
	s_add_u32 s0, s20, 0x40000
	global_load_lds_dwordx4 v134, s[20:21]
	s_mov_b32 m0, s65
	s_addc_u32 s1, s21, 0
	s_add_i32 s66, s35, 0x4000
	global_load_lds_dwordx4 v130, s[20:21]
	s_mov_b32 m0, s66
	s_add_i32 s67, s35, 0x6000
	global_load_lds_dwordx4 v134, s[0:1]
	s_mov_b32 m0, s67
	v_mov_b32_e32 v137, 0
	global_load_lds_dwordx4 v130, s[0:1]
	s_mov_b32 s98, s12
	s_mov_b32 s99, s4
	s_mov_b32 s100, s8
	v_mov_b32_e32 v240, v10
	v_mov_b32_e32 v241, v11
	v_mov_b32_e32 v242, v12
	v_mov_b32_e32 v243, v8
	v_mov_b32_e32 v244, v9

; #define PG8_STAGE(bufoff, gbase, voff) do { _Pragma("unroll") for (int _i = 0; _i < 2; ++_i) \
;         __builtin_amdgcn_global_load_lds((const unsigned*)((const char*)(gbase) + (voff)[_i]), (PG8_LAS unsigned*)(lds + (bufoff) + ldsw + _i * 8192), 16, 0, 0); } while (0)
; #define PG8_LDA(dst, b, h) do { _Pragma("unroll") for (int m = 0; m < 4; ++m) _Pragma("unroll") for (int k = 0; k < 2; ++k) dst[m][k] = *(const PG8_LAS bf16x8*)(lds + PG8_SA(b, h) + aoff + m * 2048 + k * 1024); } while (0)
; #define PG8_LDB(dst, b, h) do { _Pragma("unroll") for (int n = 0; n < 2; ++n) _Pragma("unroll") for (int k = 0; k < 2; ++k) dst[n][k] = *(const PG8_LAS bf16x8*)(lds + PG8_SB(b, h) + boff + n * 2048 + k * 1024); } while (0)
; #define PG8_MMA(ai, bj, At, Bt) do { __builtin_amdgcn_s_setprio(1); _Pragma("unroll") for (int m = 0; m < 4; ++m) _Pragma("unroll") for (int n = 0; n < 2; ++n) _Pragma("unroll") for (int k = 0; k < 2; ++k) \
;         acc[ai][bj][m][n] = __builtin_amdgcn_mfma_f32_16x16x32_bf16(Bt[n][k], At[m][k], acc[ai][bj][m][n], 0, 0, 0); __builtin_amdgcn_s_setprio(0); } while (0)
; #define PG8_WAIT_V(n) asm volatile("s_waitcnt vmcnt(" #n ")" ::: "memory")
; #define PG8_WAIT_L(n) asm volatile("s_waitcnt lgkmcnt(" #n ")" ::: "memory")
; template <class Epi, class Sched, bool ALIGN_EPI = false, bool SP2 = false>
; __device__ __forceinline__ void gemm_phase(PG8_LAS unsigned char* lds, const Gemm g, const Sched& S, const Epi& E) {
;     ...
;             const bool last = (t == nt - 2);
;             const char* a1 = cA + (size_t)(t + 1) * kstep;
;             const char* a2 = last ? nA : cA + (size_t)(t + 2) * kstep; const char* b2 = last ? nB : cB + (size_t)(t + 2) * kstep;
;             const char* a3 = a2 + kstep; const char* b3 = b2 + kstep;
;             if (last && has_next) S.a_ready(nxt);
;             if constexpr (SP2) {
;             PG8_LDB(B0, 0, 0); PG8_LDB(B1, 0, 1); PG8_SCHED; PG8_LDA(At, 0, 0); PG8_STAGE(PG8_SA(1, 1), a1 + hstep, voffA);
;             PG8_WAIT_V(8); PG8_WAIT_L(0); PG8_BAR; PG8_MMA(0, 0, At, B0); PG8_MMA(0, 1, At, B1); PG8_BAR; PG8_SCHED;
;             PG8_LDA(At, 0, 1); PG8_STAGE(PG8_SB(0, 0), b2, voffB); PG8_STAGE(PG8_SB(0, 1), b2 + hstep, voffB); PG8_STAGE(PG8_SA(0, 0), a2, voffA);
;             PG8_WAIT_V(8); PG8_WAIT_L(0); PG8_BAR; PG8_MMA(1, 0, At, B0); PG8_MMA(1, 1, At, B1); PG8_BAR; PG8_SCHED;
.LBB0_414:
	ds_read_b128 v[146:149], v165
	ds_read_b128 v[150:153], v165 offset:1024
	ds_read_b128 v[154:157], v165 offset:2048
	ds_read_b128 v[168:171], v165 offset:3072
	ds_read_b128 v[172:175], v166
	ds_read_b128 v[176:179], v166 offset:1024
	ds_read_b128 v[180:183], v166 offset:2048
	ds_read_b128 v[184:187], v166 offset:3072
	s_add_u32 s52, s20, 0xfffc0080
	s_addc_u32 s53, s21, -1
	s_cmp_eq_u32 s84, 12
	s_cselect_b32 s55, s43, s53
	s_cselect_b32 s54, s78, s52
	s_cselect_b32 s53, s19, s81
	s_cselect_b32 s52, s79, s80
	s_add_i32 m0, s35, 0xc000
	ds_read_b128 v[188:191], v167
	ds_read_b128 v[192:195], v167 offset:1024
	ds_read_b128 v[198:201], v167 offset:2048
	ds_read_b128 v[202:205], v167 offset:3072
	ds_read_b128 v[206:209], v167 offset:4096
	ds_read_b128 v[210:213], v167 offset:5120
	ds_read_b128 v[214:217], v167 offset:6144
	ds_read_b128 v[218:221], v167 offset:7168
	global_load_lds_dwordx4 v138, s[20:21]
	s_add_i32 m0, s35, 0xe000
	s_nop 0
	global_load_lds_dwordx4 v140, s[20:21]
	s_waitcnt vmcnt(8)
	s_waitcnt lgkmcnt(0)
	s_barrier
	v_mfma_f32_16x16x32_bf16 v[124:127], v[146:149], v[188:191], v[124:127]
	v_mfma_f32_16x16x32_bf16 v[120:123], v[154:157], v[188:191], v[120:123]
	v_mfma_f32_16x16x32_bf16 v[108:111], v[146:149], v[198:201], v[108:111]
	v_mfma_f32_16x16x32_bf16 v[104:107], v[154:157], v[198:201], v[104:107]
	v_mfma_f32_16x16x32_bf16 v[92:95], v[146:149], v[206:209], v[92:95]
	v_mfma_f32_16x16x32_bf16 v[88:91], v[154:157], v[206:209], v[88:91]
	v_mfma_f32_16x16x32_bf16 v[76:79], v[146:149], v[214:217], v[76:79]
	v_mfma_f32_16x16x32_bf16 v[72:75], v[154:157], v[214:217], v[72:75]
	v_mfma_f32_16x16x32_bf16 v[124:127], v[150:153], v[192:195], v[124:127]
	v_mfma_f32_16x16x32_bf16 v[120:123], v[168:171], v[192:195], v[120:123]
	v_mfma_f32_16x16x32_bf16 v[108:111], v[150:153], v[202:205], v[108:111]
	v_mfma_f32_16x16x32_bf16 v[104:107], v[168:171], v[202:205], v[104:107]
	v_mfma_f32_16x16x32_bf16 v[92:95], v[150:153], v[210:213], v[92:95]
	v_mfma_f32_16x16x32_bf16 v[88:91], v[168:171], v[210:213], v[88:91]
	v_mfma_f32_16x16x32_bf16 v[76:79], v[150:153], v[218:221], v[76:79]
	v_mfma_f32_16x16x32_bf16 v[72:75], v[168:171], v[218:221], v[72:75]
	v_mfma_f32_16x16x32_bf16 v[116:119], v[172:175], v[188:191], v[116:119]
	v_mfma_f32_16x16x32_bf16 v[112:115], v[180:183], v[188:191], v[112:115]
	v_mfma_f32_16x16x32_bf16 v[100:103], v[172:175], v[198:201], v[100:103]
	v_mfma_f32_16x16x32_bf16 v[96:99], v[180:183], v[198:201], v[96:99]
	v_mfma_f32_16x16x32_bf16 v[84:87], v[172:175], v[206:209], v[84:87]
	v_mfma_f32_16x16x32_bf16 v[80:83], v[180:183], v[206:209], v[80:83]
	v_mfma_f32_16x16x32_bf16 v[68:71], v[172:175], v[214:217], v[68:71]
	v_mfma_f32_16x16x32_bf16 v[64:67], v[180:183], v[214:217], v[64:67]
	v_mfma_f32_16x16x32_bf16 v[116:119], v[176:179], v[192:195], v[116:119]
	v_mfma_f32_16x16x32_bf16 v[112:115], v[184:187], v[192:195], v[112:115]
	v_mfma_f32_16x16x32_bf16 v[100:103], v[176:179], v[202:205], v[100:103]
	v_mfma_f32_16x16x32_bf16 v[96:99], v[184:187], v[202:205], v[96:99]
	v_mfma_f32_16x16x32_bf16 v[84:87], v[176:179], v[210:213], v[84:87]
	v_mfma_f32_16x16x32_bf16 v[80:83], v[184:187], v[210:213], v[80:83]
	v_mfma_f32_16x16x32_bf16 v[68:71], v[176:179], v[218:221], v[68:71]
	v_mfma_f32_16x16x32_bf16 v[64:67], v[184:187], v[218:221], v[64:67]
	s_barrier
	s_add_i32 s85, s72, s63
	s_add_u32 s98, s52, s8
	s_addc_u32 s99, s53, s9
	s_add_u32 s100, s54, s8
	s_addc_u32 s101, s55, s9
	s_mov_b32 m0, s85
	ds_read_b128 v[188:191], v167 offset:16384
	ds_read_b128 v[192:195], v167 offset:17408
	ds_read_b128 v[198:201], v167 offset:18432
	ds_read_b128 v[202:205], v167 offset:19456
	ds_read_b128 v[206:209], v167 offset:20480
	ds_read_b128 v[210:213], v167 offset:21504
	ds_read_b128 v[214:217], v167 offset:22528
	ds_read_b128 v[218:221], v167 offset:23552
	global_load_lds_dwordx4 v132, s[52:53]
	s_add_i32 m0, s85, 0x2000
	s_add_u32 s86, s52, 0x40000
	s_addc_u32 s87, s53, 0
	s_add_i32 s85, s73, s63
	global_load_lds_dwordx4 v128, s[52:53]
	s_mov_b32 m0, s85
	s_nop 0
	global_load_lds_dwordx4 v132, s[86:87]
	s_add_i32 m0, s85, 0x2000
	s_nop 0
	global_load_lds_dwordx4 v128, s[86:87]
	s_mov_b32 m0, s35
	s_nop 0
	global_load_lds_dwordx4 v134, s[54:55]
	s_mov_b32 m0, s65
	s_nop 0
	global_load_lds_dwordx4 v130, s[54:55]
	s_waitcnt vmcnt(8)
	s_waitcnt lgkmcnt(0)
	s_barrier
	v_mfma_f32_16x16x32_bf16 v[60:63], v[146:149], v[188:191], v[60:63]
	v_mfma_f32_16x16x32_bf16 v[56:59], v[154:157], v[188:191], v[56:59]
	v_mfma_f32_16x16x32_bf16 v[44:47], v[146:149], v[198:201], v[44:47]
	v_mfma_f32_16x16x32_bf16 v[40:43], v[154:157], v[198:201], v[40:43]
	v_mfma_f32_16x16x32_bf16 v[28:31], v[146:149], v[206:209], v[28:31]
	v_mfma_f32_16x16x32_bf16 v[24:27], v[154:157], v[206:209], v[24:27]
	v_mfma_f32_16x16x32_bf16 v[12:15], v[146:149], v[214:217], v[12:15]
	v_mfma_f32_16x16x32_bf16 v[8:11], v[154:157], v[214:217], v[8:11]
	v_mfma_f32_16x16x32_bf16 v[60:63], v[150:153], v[192:195], v[60:63]
	v_mfma_f32_16x16x32_bf16 v[56:59], v[168:171], v[192:195], v[56:59]
	v_mfma_f32_16x16x32_bf16 v[44:47], v[150:153], v[202:205], v[44:47]
	v_mfma_f32_16x16x32_bf16 v[40:43], v[168:171], v[202:205], v[40:43]
	v_mfma_f32_16x16x32_bf16 v[28:31], v[150:153], v[210:213], v[28:31]
	v_mfma_f32_16x16x32_bf16 v[24:27], v[168:171], v[210:213], v[24:27]
	v_mfma_f32_16x16x32_bf16 v[12:15], v[150:153], v[218:221], v[12:15]
	v_mfma_f32_16x16x32_bf16 v[8:11], v[168:171], v[218:221], v[8:11]
	v_mfma_f32_16x16x32_bf16 v[52:55], v[172:175], v[188:191], v[52:55]
	v_mfma_f32_16x16x32_bf16 v[48:51], v[180:183], v[188:191], v[48:51]
	v_mfma_f32_16x16x32_bf16 v[36:39], v[172:175], v[198:201], v[36:39]
	v_mfma_f32_16x16x32_bf16 v[32:35], v[180:183], v[198:201], v[32:35]
	v_mfma_f32_16x16x32_bf16 v[20:23], v[172:175], v[206:209], v[20:23]
	v_mfma_f32_16x16x32_bf16 v[16:19], v[180:183], v[206:209], v[16:19]
	v_mfma_f32_16x16x32_bf16 v[4:7], v[172:175], v[214:217], v[4:7]
	v_mfma_f32_16x16x32_bf16 v[0:3], v[180:183], v[214:217], v[0:3]
	v_mfma_f32_16x16x32_bf16 v[52:55], v[176:179], v[192:195], v[52:55]
	v_mfma_f32_16x16x32_bf16 v[48:51], v[184:187], v[192:195], v[48:51]
	v_mfma_f32_16x16x32_bf16 v[36:39], v[176:179], v[202:205], v[36:39]
	v_mfma_f32_16x16x32_bf16 v[32:35], v[184:187], v[202:205], v[32:35]
	v_mfma_f32_16x16x32_bf16 v[20:23], v[176:179], v[210:213], v[20:23]
	v_mfma_f32_16x16x32_bf16 v[16:19], v[184:187], v[210:213], v[16:19]
	v_mfma_f32_16x16x32_bf16 v[4:7], v[176:179], v[218:221], v[4:7]
	v_mfma_f32_16x16x32_bf16 v[0:3], v[184:187], v[218:221], v[0:3]
	s_barrier
; #define PG8_STAGE(bufoff, gbase, voff) do { _Pragma("unroll") for (int _i = 0; _i < 2; ++_i) \
;         __builtin_amdgcn_global_load_lds((const unsigned*)((const char*)(gbase) + (voff)[_i]), (PG8_LAS unsigned*)(lds + (bufoff) + ldsw + _i * 8192), 16, 0, 0); } while (0)
; #define PG8_LDA(dst, b, h) do { _Pragma("unroll") for (int m = 0; m < 4; ++m) _Pragma("unroll") for (int k = 0; k < 2; ++k) dst[m][k] = *(const PG8_LAS bf16x8*)(lds + PG8_SA(b, h) + aoff + m * 2048 + k * 1024); } while (0)
; #define PG8_LDB(dst, b, h) do { _Pragma("unroll") for (int n = 0; n < 2; ++n) _Pragma("unroll") for (int k = 0; k < 2; ++k) dst[n][k] = *(const PG8_LAS bf16x8*)(lds + PG8_SB(b, h) + boff + n * 2048 + k * 1024); } while (0)
; #define PG8_MMA(ai, bj, At, Bt) do { __builtin_amdgcn_s_setprio(1); _Pragma("unroll") for (int m = 0; m < 4; ++m) _Pragma("unroll") for (int n = 0; n < 2; ++n) _Pragma("unroll") for (int k = 0; k < 2; ++k) \
;         acc[ai][bj][m][n] = __builtin_amdgcn_mfma_f32_16x16x32_bf16(Bt[n][k], At[m][k], acc[ai][bj][m][n], 0, 0, 0); __builtin_amdgcn_s_setprio(0); } while (0)
; #define PG8_WAIT_V(n) asm volatile("s_waitcnt vmcnt(" #n ")" ::: "memory")
; #define PG8_WAIT_L(n) asm volatile("s_waitcnt lgkmcnt(" #n ")" ::: "memory")
; #define PG8_BAR __builtin_amdgcn_s_barrier()
; #define PG8_SCHED __builtin_amdgcn_sched_barrier(0)
; template <class Epi, class Sched, bool ALIGN_EPI = false, bool SP2 = false>
; __device__ __forceinline__ void gemm_phase(PG8_LAS unsigned char* lds, const Gemm g, const Sched& S, const Epi& E) {
;     ...
;             PG8_LDB(B0, 1, 0); PG8_LDB(B1, 1, 1); PG8_SCHED; PG8_LDA(At, 1, 0); PG8_STAGE(PG8_SA(0, 1), a2 + hstep, voffA);
;             PG8_WAIT_V(8); PG8_WAIT_L(0); PG8_BAR; PG8_MMA(0, 0, At, B0); PG8_MMA(0, 1, At, B1); PG8_BAR; PG8_SCHED;
;             PG8_LDA(At, 1, 1); PG8_STAGE(PG8_SB(1, 0), b3, voffB); PG8_STAGE(PG8_SB(1, 1), b3 + hstep, voffB); PG8_STAGE(PG8_SA(1, 0), a3, voffA);
;             PG8_WAIT_V(8); PG8_WAIT_L(0); PG8_BAR; PG8_MMA(1, 0, At, B0); PG8_MMA(1, 1, At, B1); PG8_BAR; PG8_SCHED;
	s_add_i32 s85, 0, 0x18000
	v_add_u32_e32 v136, s85, v161
	s_add_i32 s86, 0, 0x1c000
	ds_read_b128 v[146:149], v136
	ds_read_b128 v[150:153], v136 offset:1024
	ds_read_b128 v[154:157], v136 offset:2048
	ds_read_b128 v[168:171], v136 offset:3072
	v_add_u32_e32 v136, s86, v161
	ds_read_b128 v[172:175], v136
	ds_read_b128 v[176:179], v136 offset:1024
	ds_read_b128 v[180:183], v136 offset:2048
	ds_read_b128 v[184:187], v136 offset:3072
	s_add_u32 s54, s54, 0x40000
	s_addc_u32 s55, s55, 0
	s_mov_b32 m0, s66
	ds_read_b128 v[188:191], v167 offset:32768
	ds_read_b128 v[192:195], v167 offset:33792
	ds_read_b128 v[198:201], v167 offset:34816
	ds_read_b128 v[202:205], v167 offset:35840
	ds_read_b128 v[206:209], v167 offset:36864
	ds_read_b128 v[210:213], v167 offset:37888
	ds_read_b128 v[214:217], v167 offset:38912
	ds_read_b128 v[218:221], v167 offset:39936
	global_load_lds_dwordx4 v134, s[54:55]
	s_mov_b32 m0, s67
	s_nop 0
	global_load_lds_dwordx4 v130, s[54:55]
	s_waitcnt vmcnt(8)
	s_waitcnt lgkmcnt(0)
	s_barrier
	v_mfma_f32_16x16x32_bf16 v[124:127], v[146:149], v[188:191], v[124:127]
	v_mfma_f32_16x16x32_bf16 v[120:123], v[154:157], v[188:191], v[120:123]
	v_mfma_f32_16x16x32_bf16 v[108:111], v[146:149], v[198:201], v[108:111]
	v_mfma_f32_16x16x32_bf16 v[104:107], v[154:157], v[198:201], v[104:107]
	v_mfma_f32_16x16x32_bf16 v[92:95], v[146:149], v[206:209], v[92:95]
	v_mfma_f32_16x16x32_bf16 v[88:91], v[154:157], v[206:209], v[88:91]
	v_mfma_f32_16x16x32_bf16 v[76:79], v[146:149], v[214:217], v[76:79]
	v_mfma_f32_16x16x32_bf16 v[72:75], v[154:157], v[214:217], v[72:75]
	v_mfma_f32_16x16x32_bf16 v[124:127], v[150:153], v[192:195], v[124:127]
	v_mfma_f32_16x16x32_bf16 v[120:123], v[168:171], v[192:195], v[120:123]
	v_mfma_f32_16x16x32_bf16 v[108:111], v[150:153], v[202:205], v[108:111]
	v_mfma_f32_16x16x32_bf16 v[104:107], v[168:171], v[202:205], v[104:107]
	v_mfma_f32_16x16x32_bf16 v[92:95], v[150:153], v[210:213], v[92:95]
	v_mfma_f32_16x16x32_bf16 v[88:91], v[168:171], v[210:213], v[88:91]
	v_mfma_f32_16x16x32_bf16 v[76:79], v[150:153], v[218:221], v[76:79]
	v_mfma_f32_16x16x32_bf16 v[72:75], v[168:171], v[218:221], v[72:75]
	v_mfma_f32_16x16x32_bf16 v[116:119], v[172:175], v[188:191], v[116:119]
	v_mfma_f32_16x16x32_bf16 v[112:115], v[180:183], v[188:191], v[112:115]
	v_mfma_f32_16x16x32_bf16 v[100:103], v[172:175], v[198:201], v[100:103]
	v_mfma_f32_16x16x32_bf16 v[96:99], v[180:183], v[198:201], v[96:99]
	v_mfma_f32_16x16x32_bf16 v[84:87], v[172:175], v[206:209], v[84:87]
	v_mfma_f32_16x16x32_bf16 v[80:83], v[180:183], v[206:209], v[80:83]
	v_mfma_f32_16x16x32_bf16 v[68:71], v[172:175], v[214:217], v[68:71]
	v_mfma_f32_16x16x32_bf16 v[64:67], v[180:183], v[214:217], v[64:67]
	v_mfma_f32_16x16x32_bf16 v[116:119], v[176:179], v[192:195], v[116:119]
	v_mfma_f32_16x16x32_bf16 v[112:115], v[184:187], v[192:195], v[112:115]
	v_mfma_f32_16x16x32_bf16 v[100:103], v[176:179], v[202:205], v[100:103]
	v_mfma_f32_16x16x32_bf16 v[96:99], v[184:187], v[202:205], v[96:99]
	v_mfma_f32_16x16x32_bf16 v[84:87], v[176:179], v[210:213], v[84:87]
	v_mfma_f32_16x16x32_bf16 v[80:83], v[184:187], v[210:213], v[80:83]
	v_mfma_f32_16x16x32_bf16 v[68:71], v[176:179], v[218:221], v[68:71]
	v_mfma_f32_16x16x32_bf16 v[64:67], v[184:187], v[218:221], v[64:67]
	s_barrier
	s_add_i32 s54, s85, s63
	s_mov_b32 m0, s54
	ds_read_b128 v[188:191], v167 offset:49152
	ds_read_b128 v[192:195], v167 offset:50176
	ds_read_b128 v[198:201], v167 offset:51200
	ds_read_b128 v[202:205], v167 offset:52224
	ds_read_b128 v[206:209], v167 offset:53248
	ds_read_b128 v[210:213], v167 offset:54272
	ds_read_b128 v[214:217], v167 offset:55296
	ds_read_b128 v[218:221], v167 offset:56320
	global_load_lds_dwordx4 v132, s[98:99]
	s_add_i32 m0, s54, 0x2000
	s_add_u32 s52, s52, 0x40080
	s_addc_u32 s53, s53, 0
	s_add_i32 s54, s86, s63
	global_load_lds_dwordx4 v128, s[98:99]
	s_mov_b32 m0, s54
	s_nop 0
	global_load_lds_dwordx4 v132, s[52:53]
	s_add_i32 m0, s54, 0x2000
	s_nop 0
	global_load_lds_dwordx4 v128, s[52:53]
	s_mov_b32 m0, s69
	s_nop 0
	global_load_lds_dwordx4 v134, s[100:101]
	s_mov_b32 m0, s70
	s_nop 0
	global_load_lds_dwordx4 v130, s[100:101]
	s_waitcnt vmcnt(8)
	s_waitcnt lgkmcnt(0)
	s_barrier
	v_mfma_f32_16x16x32_bf16 v[60:63], v[146:149], v[188:191], v[60:63]
	v_mfma_f32_16x16x32_bf16 v[56:59], v[154:157], v[188:191], v[56:59]
	v_mfma_f32_16x16x32_bf16 v[44:47], v[146:149], v[198:201], v[44:47]
	v_mfma_f32_16x16x32_bf16 v[40:43], v[154:157], v[198:201], v[40:43]
	v_mfma_f32_16x16x32_bf16 v[28:31], v[146:149], v[206:209], v[28:31]
	v_mfma_f32_16x16x32_bf16 v[24:27], v[154:157], v[206:209], v[24:27]
	v_mfma_f32_16x16x32_bf16 v[12:15], v[146:149], v[214:217], v[12:15]
	v_mfma_f32_16x16x32_bf16 v[8:11], v[154:157], v[214:217], v[8:11]
	v_mfma_f32_16x16x32_bf16 v[60:63], v[150:153], v[192:195], v[60:63]
	v_mfma_f32_16x16x32_bf16 v[56:59], v[168:171], v[192:195], v[56:59]
	v_mfma_f32_16x16x32_bf16 v[44:47], v[150:153], v[202:205], v[44:47]
	v_mfma_f32_16x16x32_bf16 v[40:43], v[168:171], v[202:205], v[40:43]
	v_mfma_f32_16x16x32_bf16 v[28:31], v[150:153], v[210:213], v[28:31]
	v_mfma_f32_16x16x32_bf16 v[24:27], v[168:171], v[210:213], v[24:27]
	v_mfma_f32_16x16x32_bf16 v[12:15], v[150:153], v[218:221], v[12:15]
	v_mfma_f32_16x16x32_bf16 v[8:11], v[168:171], v[218:221], v[8:11]
	v_mfma_f32_16x16x32_bf16 v[52:55], v[172:175], v[188:191], v[52:55]
	v_mfma_f32_16x16x32_bf16 v[48:51], v[180:183], v[188:191], v[48:51]
	v_mfma_f32_16x16x32_bf16 v[36:39], v[172:175], v[198:201], v[36:39]
	v_mfma_f32_16x16x32_bf16 v[32:35], v[180:183], v[198:201], v[32:35]
	v_mfma_f32_16x16x32_bf16 v[20:23], v[172:175], v[206:209], v[20:23]
	v_mfma_f32_16x16x32_bf16 v[16:19], v[180:183], v[206:209], v[16:19]
	v_mfma_f32_16x16x32_bf16 v[4:7], v[172:175], v[214:217], v[4:7]
	v_mfma_f32_16x16x32_bf16 v[0:3], v[180:183], v[214:217], v[0:3]
	v_mfma_f32_16x16x32_bf16 v[52:55], v[176:179], v[192:195], v[52:55]
	v_mfma_f32_16x16x32_bf16 v[48:51], v[184:187], v[192:195], v[48:51]
	v_mfma_f32_16x16x32_bf16 v[36:39], v[176:179], v[202:205], v[36:39]
	v_mfma_f32_16x16x32_bf16 v[32:35], v[184:187], v[202:205], v[32:35]
	v_mfma_f32_16x16x32_bf16 v[20:23], v[176:179], v[210:213], v[20:23]
	v_mfma_f32_16x16x32_bf16 v[16:19], v[184:187], v[210:213], v[16:19]
	v_mfma_f32_16x16x32_bf16 v[4:7], v[176:179], v[218:221], v[4:7]
	v_mfma_f32_16x16x32_bf16 v[0:3], v[184:187], v[218:221], v[0:3]
	s_barrier
	s_add_i32 s84, s84, 2
	s_add_u32 s20, s20, 0x100
	s_addc_u32 s21, s21, 0
	s_add_u32 s80, s80, 0x100
	s_addc_u32 s81, s81, 0
	s_cmp_gt_u32 s84, 13
	s_cbranch_scc0 .LBB0_414
	v_readlane_b32 s101, v249, 49
	s_nop 3
	s_cmp_eq_u32 s101, 0
	s_cbranch_scc1 .Ldw_done_0
	s_add_u32 s98, s28, 0x183500
	s_addc_u32 s99, s29, 0
	v_mov_b32_e32 v251, 0
	s_mov_b32 s100, 0
; #define PG8_BAR __builtin_amdgcn_s_barrier()
; template <class Epi, class Sched, bool ALIGN_EPI = false, bool SP2 = false>
; __device__ __forceinline__ void gemm_phase(PG8_LAS unsigned char* lds, const Gemm g, const Sched& S, const Epi& E) {
;     ...
;         if constexpr (ALIGN_EPI) { if (wr == 0) PG8_BAR; }
.Ldw_poll_0:
	global_load_dword v250, v251, s[98:99] sc1
	s_waitcnt vmcnt(0)
	v_cmp_le_u32_e32 vcc, s101, v250
	s_cbranch_vccnz .Ldw_ok_0
	s_sleep 2
	s_add_i32 s100, s100, 1
	s_cmp_lt_u32 s100, 0x2000
	s_cbranch_scc1 .Ldw_poll_0
.Ldw_ok_0:
	s_mov_b32 s101, 0
	v_writelane_b32 v249, s101, 49
.Ldw_done_0:
	s_and_b64 vcc, exec, s[10:11]
	s_cbranch_vccz .LBB0_417
	s_barrier

; #define PG8_LAS __attribute__((address_space(3)))
; #define PG8_STAGE(bufoff, gbase, voff) do { _Pragma("unroll") for (int _i = 0; _i < 2; ++_i) \
;         __builtin_amdgcn_global_load_lds((const unsigned*)((const char*)(gbase) + (voff)[_i]), (PG8_LAS unsigned*)(lds + (bufoff) + ldsw + _i * 8192), 16, 0, 0); } while (0)
;     __host__ __device__ bool next(int i, Unit& u) const {
;         const long L = (long)i * G + c; if (L >= nwg) return false;
;         int wgid = (int)L; { const int q = nwg / NXCD, r = nwg % NXCD, xcd = wgid % NXCD, off = wgid / NXCD; wgid = (xcd < r ? xcd * (q + 1) : r * (q + 1) + (xcd - r) * q) + off; }
;         const int nig = WGM * nN, gid = wgid / nig, fm = gid * WGM, gsz = (nM - fm) < WGM ? (nM - fm) : WGM;
;         u.pm = fm + ((wgid % nig) % gsz); u.pn = (wgid % nig) / gsz; return true;
;     }
; __device__ __forceinline__ unsigned cvt_pk_bf16(float lo, float hi) { unsigned r; asm volatile("v_cvt_pk_bf16_f32 %0, %1, %2" : "=v"(r) : "v"(lo), "v"(hi)); return r; }
; template <class Epi, class Sched, bool ALIGN_EPI = false, bool SP2 = false>
; __device__ __forceinline__ void gemm_phase(PG8_LAS unsigned char* lds, const Gemm g, const Sched& S, const Epi& E) {
;     const int tid = threadIdx.x, wid = __builtin_amdgcn_readfirstlane(tid >> 6), lane = tid & 63, wr = wid >> 2, wc = wid & 3, fr = lane & 15, fq = lane >> 4;
;     const int K = g.K, nt = K / BK;
;     unsigned voffA[2], voffB[2];
; #pragma unroll
;     for (int i = 0; i < 2; ++i) { int R, C; stage_rc(tid * 16 + i * 8192, R, C); const int Rb = Epi::PERM ? ((R & ~31) + perm32(R & 31)) : R;
;         voffA[i] = (unsigned)(R * K + C) * 2u; voffB[i] = (unsigned)(Rb * K + C) * 2u; }
;     ...
;     const char* cA = (const char*)g.A + (size_t)cur.pm * tstep; const char* cB = (const char*)g.Bt + (size_t)cur.pn * tstep;
;     S.a_ready(cur);
;     if constexpr (SP2) {
;         PG8_STAGE(PG8_SB(0, 0), cB, voffB); PG8_STAGE(PG8_SB(0, 1), cB + hstep, voffB); PG8_STAGE(PG8_SA(0, 0), cA, voffA); PG8_STAGE(PG8_SA(0, 1), cA + hstep, voffA);
.LBB0_782:
	v_readlane_b32 s101, v249, 48
	s_nop 3
	s_cmp_lg_u32 s101, 0
	s_cselect_b32 s101, 3, 0
	v_writelane_b32 v249, s101, 49
	s_cmp_lt_i32 s30, 9
	s_cselect_b64 s[0:1], -1, 0
	s_and_b64 s[6:7], s[0:1], s[4:5]
	s_andn2_b64 vcc, exec, s[6:7]
	s_cbranch_vccnz .LBB0_817
	s_ashr_i32 s3, s2, 31
	s_cmpk_lt_i32 s2, 0xb00
	s_cbranch_scc0 .Lpro_skip_2
	v_readfirstlane_b32 s5, v197
	s_nop 3
	v_lshrrev_b32_e32 v0, 5, v197
	v_lshrrev_b32_e32 v2, 1, v197
	v_and_b32_e32 v0, 4, v0
	v_bfe_u32 v1, v197, 2, 2
	v_and_b32_e32 v11, 24, v2
	v_or3_b32 v0, v0, v1, v11
	v_lshlrev_b32_e32 v1, 4, v197
	v_add_u32_e32 v8, 0x2000, v1
	v_lshrrev_b32_e32 v2, 7, v8
	s_movk_i32 s0, 0xe0
	v_and_b32_e32 v4, 32, v197
	v_and_or_b32 v3, v2, s0, v0
	v_bitop3_b32 v9, v1, v4, 48 bitop3:0x6c
	v_and_b32_e32 v10, 64, v197
	v_bfe_u32 v12, v197, 2, 4
	s_movk_i32 s0, 0xf0
	v_or_b32_e32 v1, v9, v10
	v_and_or_b32 v2, v2, s0, v12
	v_lshl_or_b32 v130, v2, 11, v1
	v_lshrrev_b32_e32 v2, 3, v197
	s_movk_i32 s0, 0x60
	s_add_u32 s50, s28, 0x1300000
	v_and_or_b32 v0, v2, s0, v0
	s_movk_i32 s0, 0x70
	s_addc_u32 s51, s29, 0
	v_lshl_or_b32 v132, v0, 11, v1
	v_and_or_b32 v0, v2, s0, v12
	s_lshr_b32 s0, s3, 29
	s_add_i32 s0, s2, s0
	s_lshr_b32 s8, s5, 6
	s_ashr_i32 s1, s0, 3
	s_and_b32 s0, s0, -8
	s_lshr_b32 s12, s5, 8
	s_lshl_b32 s52, s8, 10
	s_sub_i32 s0, s2, s0
	s_cmp_lt_i32 s0, 0
	s_movk_i32 s53, 0x161
	s_cselect_b32 s4, s53, 0x160
	s_mul_i32 s0, s4, s0
	s_add_i32 s0, s0, s1
	s_mul_hi_i32 s1, s0, 0x2e8ba2e9
	s_lshr_b32 s4, s1, 31
	s_ashr_i32 s1, s1, 5
	s_add_i32 s1, s1, s4
	s_lshl_b32 s9, s1, 3
	s_mulk_i32 s1, 0xb0
	s_sub_i32 s0, s0, s1
	s_sext_i32_i16 s1, s0
	s_bfe_u32 s1, s1, 0x3001c
	s_add_i32 s1, s0, s1
	s_sext_i32_i16 s4, s1
	s_and_b32 s1, s1, 0xfff8
	s_sub_i32 s0, s0, s1
	s_sext_i32_i16 s0, s0
	s_lshr_b32 s4, s4, 3
	s_add_i32 s34, s9, s0
	s_ashr_i32 s35, s34, 31
	s_bfe_i64 s[10:11], s[4:5], 0x100000
	s_lshl_b64 s[0:1], s[34:35], 19
	s_lshl_b64 s[10:11], s[10:11], 19
	s_add_u32 s38, s50, s10
	s_addc_u32 s39, s51, s11
	s_add_i32 s35, s52, 0
	s_add_i32 m0, s35, 0x10000
	v_lshl_or_b32 v128, v3, 11, v1
	global_load_lds_dwordx4 v132, s[38:39]
	s_add_i32 m0, s35, 0x12000
	s_add_u32 s10, s38, 0x40000
	global_load_lds_dwordx4 v128, s[38:39]
	s_addc_u32 s11, s39, 0
	s_add_i32 m0, s35, 0x14000
	v_lshl_or_b32 v134, v0, 11, v1
	global_load_lds_dwordx4 v132, s[10:11]
	s_add_i32 m0, s35, 0x16000
	s_add_u32 s20, s36, s0
	s_addc_u32 s21, s37, s1
	s_add_i32 s54, s35, 0x2000
	global_load_lds_dwordx4 v128, s[10:11]
	s_mov_b32 m0, s35
	s_add_u32 s0, s20, 0x40000
	global_load_lds_dwordx4 v134, s[20:21]
	s_mov_b32 m0, s54
	s_addc_u32 s1, s21, 0
	s_add_i32 s55, s35, 0x4000
	global_load_lds_dwordx4 v130, s[20:21]
	s_mov_b32 m0, s55
	s_add_i32 s56, s35, 0x6000
	global_load_lds_dwordx4 v134, s[0:1]
	s_mov_b32 m0, s56
	v_mov_b32_e32 v133, 0
	global_load_lds_dwordx4 v130, s[0:1]
	s_mov_b32 s98, s12
	s_mov_b32 s99, s4
	s_mov_b32 s100, s8
	v_mov_b32_e32 v240, v10
	v_mov_b32_e32 v241, v11
	v_mov_b32_e32 v242, v12
	v_mov_b32_e32 v243, v8
	v_mov_b32_e32 v244, v9

; #define PG8_STAGE(bufoff, gbase, voff) do { _Pragma("unroll") for (int _i = 0; _i < 2; ++_i) \
;         __builtin_amdgcn_global_load_lds((const unsigned*)((const char*)(gbase) + (voff)[_i]), (PG8_LAS unsigned*)(lds + (bufoff) + ldsw + _i * 8192), 16, 0, 0); } while (0)
; #define PG8_LDA(dst, b, h) do { _Pragma("unroll") for (int m = 0; m < 4; ++m) _Pragma("unroll") for (int k = 0; k < 2; ++k) dst[m][k] = *(const PG8_LAS bf16x8*)(lds + PG8_SA(b, h) + aoff + m * 2048 + k * 1024); } while (0)
; #define PG8_LDB(dst, b, h) do { _Pragma("unroll") for (int n = 0; n < 2; ++n) _Pragma("unroll") for (int k = 0; k < 2; ++k) dst[n][k] = *(const PG8_LAS bf16x8*)(lds + PG8_SB(b, h) + boff + n * 2048 + k * 1024); } while (0)
; #define PG8_MMA(ai, bj, At, Bt) do { __builtin_amdgcn_s_setprio(1); _Pragma("unroll") for (int m = 0; m < 4; ++m) _Pragma("unroll") for (int n = 0; n < 2; ++n) _Pragma("unroll") for (int k = 0; k < 2; ++k) \
;         acc[ai][bj][m][n] = __builtin_amdgcn_mfma_f32_16x16x32_bf16(Bt[n][k], At[m][k], acc[ai][bj][m][n], 0, 0, 0); __builtin_amdgcn_s_setprio(0); } while (0)
; #define PG8_WAIT_V(n) asm volatile("s_waitcnt vmcnt(" #n ")" ::: "memory")
; #define PG8_WAIT_L(n) asm volatile("s_waitcnt lgkmcnt(" #n ")" ::: "memory")
; template <class Epi, class Sched, bool ALIGN_EPI = false, bool SP2 = false>
; __device__ __forceinline__ void gemm_phase(PG8_LAS unsigned char* lds, const Gemm g, const Sched& S, const Epi& E) {
;     ...
;             const bool last = (t == nt - 2);
;             const char* a1 = cA + (size_t)(t + 1) * kstep;
;             const char* a2 = last ? nA : cA + (size_t)(t + 2) * kstep; const char* b2 = last ? nB : cB + (size_t)(t + 2) * kstep;
;             const char* a3 = a2 + kstep; const char* b3 = b2 + kstep;
;             if (last && has_next) S.a_ready(nxt);
;             if constexpr (SP2) {
;             PG8_LDB(B0, 0, 0); PG8_LDB(B1, 0, 1); PG8_SCHED; PG8_LDA(At, 0, 0); PG8_STAGE(PG8_SA(1, 1), a1 + hstep, voffA);
;             PG8_WAIT_V(8); PG8_WAIT_L(0); PG8_BAR; PG8_MMA(0, 0, At, B0); PG8_MMA(0, 1, At, B1); PG8_BAR; PG8_SCHED;
;             PG8_LDA(At, 0, 1); PG8_STAGE(PG8_SB(0, 0), b2, voffB); PG8_STAGE(PG8_SB(0, 1), b2 + hstep, voffB); PG8_STAGE(PG8_SA(0, 0), a2, voffA);
;             PG8_WAIT_V(8); PG8_WAIT_L(0); PG8_BAR; PG8_MMA(1, 0, At, B0); PG8_MMA(1, 1, At, B1); PG8_BAR; PG8_SCHED;
.LBB0_810:
	ds_read_b128 v[154:157], v150
	ds_read_b128 v[158:161], v150 offset:1024
	ds_read_b128 v[162:165], v150 offset:2048
	ds_read_b128 v[166:169], v150 offset:3072
	ds_read_b128 v[170:173], v151
	ds_read_b128 v[174:177], v151 offset:1024
	ds_read_b128 v[178:181], v151 offset:2048
	ds_read_b128 v[182:185], v151 offset:3072
	s_add_u32 s38, s20, 0xfffc0080
	s_addc_u32 s39, s21, -1
	s_cmp_eq_u32 s69, 12
	s_cselect_b32 s45, s15, s39
	s_cselect_b32 s44, s65, s38
	s_cselect_b32 s39, s13, s68
	s_cselect_b32 s38, s66, s67
	s_add_i32 m0, s35, 0xc000
	ds_read_b128 v[186:189], v152
	ds_read_b128 v[190:193], v152 offset:1024
	ds_read_b128 v[198:201], v152 offset:2048
	ds_read_b128 v[202:205], v152 offset:3072
	ds_read_b128 v[206:209], v152 offset:4096
	ds_read_b128 v[210:213], v152 offset:5120
	ds_read_b128 v[214:217], v152 offset:6144
	ds_read_b128 v[218:221], v152 offset:7168
	global_load_lds_dwordx4 v136, s[20:21]
	s_add_i32 m0, s35, 0xe000
	s_nop 0
	global_load_lds_dwordx4 v138, s[20:21]
	s_waitcnt vmcnt(8)
	s_waitcnt lgkmcnt(0)
	s_barrier
	v_mfma_f32_16x16x32_bf16 v[124:127], v[154:157], v[186:189], v[124:127]
	v_mfma_f32_16x16x32_bf16 v[116:119], v[162:165], v[186:189], v[116:119]
	v_mfma_f32_16x16x32_bf16 v[108:111], v[154:157], v[198:201], v[108:111]
	v_mfma_f32_16x16x32_bf16 v[100:103], v[162:165], v[198:201], v[100:103]
	v_mfma_f32_16x16x32_bf16 v[92:95], v[154:157], v[206:209], v[92:95]
	v_mfma_f32_16x16x32_bf16 v[84:87], v[162:165], v[206:209], v[84:87]
	v_mfma_f32_16x16x32_bf16 v[76:79], v[154:157], v[214:217], v[76:79]
	v_mfma_f32_16x16x32_bf16 v[68:71], v[162:165], v[214:217], v[68:71]
	v_mfma_f32_16x16x32_bf16 v[124:127], v[158:161], v[190:193], v[124:127]
	v_mfma_f32_16x16x32_bf16 v[116:119], v[166:169], v[190:193], v[116:119]
	v_mfma_f32_16x16x32_bf16 v[108:111], v[158:161], v[202:205], v[108:111]
	v_mfma_f32_16x16x32_bf16 v[100:103], v[166:169], v[202:205], v[100:103]
	v_mfma_f32_16x16x32_bf16 v[92:95], v[158:161], v[210:213], v[92:95]
	v_mfma_f32_16x16x32_bf16 v[84:87], v[166:169], v[210:213], v[84:87]
	v_mfma_f32_16x16x32_bf16 v[76:79], v[158:161], v[218:221], v[76:79]
	v_mfma_f32_16x16x32_bf16 v[68:71], v[166:169], v[218:221], v[68:71]
	v_mfma_f32_16x16x32_bf16 v[120:123], v[170:173], v[186:189], v[120:123]
	v_mfma_f32_16x16x32_bf16 v[112:115], v[178:181], v[186:189], v[112:115]
	v_mfma_f32_16x16x32_bf16 v[104:107], v[170:173], v[198:201], v[104:107]
	v_mfma_f32_16x16x32_bf16 v[96:99], v[178:181], v[198:201], v[96:99]
	v_mfma_f32_16x16x32_bf16 v[88:91], v[170:173], v[206:209], v[88:91]
	v_mfma_f32_16x16x32_bf16 v[80:83], v[178:181], v[206:209], v[80:83]
	v_mfma_f32_16x16x32_bf16 v[72:75], v[170:173], v[214:217], v[72:75]
	v_mfma_f32_16x16x32_bf16 v[64:67], v[178:181], v[214:217], v[64:67]
	v_mfma_f32_16x16x32_bf16 v[120:123], v[174:177], v[190:193], v[120:123]
	v_mfma_f32_16x16x32_bf16 v[112:115], v[182:185], v[190:193], v[112:115]
	v_mfma_f32_16x16x32_bf16 v[104:107], v[174:177], v[202:205], v[104:107]
	v_mfma_f32_16x16x32_bf16 v[96:99], v[182:185], v[202:205], v[96:99]
	v_mfma_f32_16x16x32_bf16 v[88:91], v[174:177], v[210:213], v[88:91]
	v_mfma_f32_16x16x32_bf16 v[80:83], v[182:185], v[210:213], v[80:83]
	v_mfma_f32_16x16x32_bf16 v[72:75], v[174:177], v[218:221], v[72:75]
	v_mfma_f32_16x16x32_bf16 v[64:67], v[182:185], v[218:221], v[64:67]
	s_barrier
	s_add_i32 s70, s60, s52
	s_add_u32 s98, s38, s8
	s_addc_u32 s99, s39, s9
	s_add_u32 s100, s44, s8
	s_addc_u32 s101, s45, s9
	s_mov_b32 m0, s70
	ds_read_b128 v[186:189], v152 offset:16384
	ds_read_b128 v[190:193], v152 offset:17408
	ds_read_b128 v[198:201], v152 offset:18432
	ds_read_b128 v[202:205], v152 offset:19456
	ds_read_b128 v[206:209], v152 offset:20480
	ds_read_b128 v[210:213], v152 offset:21504
	ds_read_b128 v[214:217], v152 offset:22528
	ds_read_b128 v[218:221], v152 offset:23552
	global_load_lds_dwordx4 v132, s[38:39]
	s_add_i32 m0, s70, 0x2000
	s_add_u32 s70, s38, 0x40000
	s_addc_u32 s71, s39, 0
	s_add_i32 s72, s61, s52
	global_load_lds_dwordx4 v128, s[38:39]
	s_mov_b32 m0, s72
	s_nop 0
	global_load_lds_dwordx4 v132, s[70:71]
	s_add_i32 m0, s72, 0x2000
	s_nop 0
	global_load_lds_dwordx4 v128, s[70:71]
	s_mov_b32 m0, s35
	s_nop 0
	global_load_lds_dwordx4 v134, s[44:45]
	s_mov_b32 m0, s54
	s_nop 0
	global_load_lds_dwordx4 v130, s[44:45]
	s_waitcnt vmcnt(8)
	s_waitcnt lgkmcnt(0)
	s_barrier
	v_mfma_f32_16x16x32_bf16 v[60:63], v[154:157], v[186:189], v[60:63]
	v_mfma_f32_16x16x32_bf16 v[52:55], v[162:165], v[186:189], v[52:55]
	v_mfma_f32_16x16x32_bf16 v[44:47], v[154:157], v[198:201], v[44:47]
	v_mfma_f32_16x16x32_bf16 v[36:39], v[162:165], v[198:201], v[36:39]
	v_mfma_f32_16x16x32_bf16 v[28:31], v[154:157], v[206:209], v[28:31]
	v_mfma_f32_16x16x32_bf16 v[20:23], v[162:165], v[206:209], v[20:23]
	v_mfma_f32_16x16x32_bf16 v[12:15], v[154:157], v[214:217], v[12:15]
	v_mfma_f32_16x16x32_bf16 v[4:7], v[162:165], v[214:217], v[4:7]
	v_mfma_f32_16x16x32_bf16 v[60:63], v[158:161], v[190:193], v[60:63]
	v_mfma_f32_16x16x32_bf16 v[52:55], v[166:169], v[190:193], v[52:55]
	v_mfma_f32_16x16x32_bf16 v[44:47], v[158:161], v[202:205], v[44:47]
	v_mfma_f32_16x16x32_bf16 v[36:39], v[166:169], v[202:205], v[36:39]
	v_mfma_f32_16x16x32_bf16 v[28:31], v[158:161], v[210:213], v[28:31]
	v_mfma_f32_16x16x32_bf16 v[20:23], v[166:169], v[210:213], v[20:23]
	v_mfma_f32_16x16x32_bf16 v[12:15], v[158:161], v[218:221], v[12:15]
	v_mfma_f32_16x16x32_bf16 v[4:7], v[166:169], v[218:221], v[4:7]
	v_mfma_f32_16x16x32_bf16 v[56:59], v[170:173], v[186:189], v[56:59]
	v_mfma_f32_16x16x32_bf16 v[48:51], v[178:181], v[186:189], v[48:51]
	v_mfma_f32_16x16x32_bf16 v[40:43], v[170:173], v[198:201], v[40:43]
	v_mfma_f32_16x16x32_bf16 v[32:35], v[178:181], v[198:201], v[32:35]
	v_mfma_f32_16x16x32_bf16 v[24:27], v[170:173], v[206:209], v[24:27]
	v_mfma_f32_16x16x32_bf16 v[16:19], v[178:181], v[206:209], v[16:19]
	v_mfma_f32_16x16x32_bf16 v[8:11], v[170:173], v[214:217], v[8:11]
	v_mfma_f32_16x16x32_bf16 v[0:3], v[178:181], v[214:217], v[0:3]
	v_mfma_f32_16x16x32_bf16 v[56:59], v[174:177], v[190:193], v[56:59]
	v_mfma_f32_16x16x32_bf16 v[48:51], v[182:185], v[190:193], v[48:51]
	v_mfma_f32_16x16x32_bf16 v[40:43], v[174:177], v[202:205], v[40:43]
	v_mfma_f32_16x16x32_bf16 v[32:35], v[182:185], v[202:205], v[32:35]
	v_mfma_f32_16x16x32_bf16 v[24:27], v[174:177], v[210:213], v[24:27]
	v_mfma_f32_16x16x32_bf16 v[16:19], v[182:185], v[210:213], v[16:19]
	v_mfma_f32_16x16x32_bf16 v[8:11], v[174:177], v[218:221], v[8:11]
	v_mfma_f32_16x16x32_bf16 v[0:3], v[182:185], v[218:221], v[0:3]
	s_barrier
; #define PG8_STAGE(bufoff, gbase, voff) do { _Pragma("unroll") for (int _i = 0; _i < 2; ++_i) \
;         __builtin_amdgcn_global_load_lds((const unsigned*)((const char*)(gbase) + (voff)[_i]), (PG8_LAS unsigned*)(lds + (bufoff) + ldsw + _i * 8192), 16, 0, 0); } while (0)
; #define PG8_LDA(dst, b, h) do { _Pragma("unroll") for (int m = 0; m < 4; ++m) _Pragma("unroll") for (int k = 0; k < 2; ++k) dst[m][k] = *(const PG8_LAS bf16x8*)(lds + PG8_SA(b, h) + aoff + m * 2048 + k * 1024); } while (0)
; #define PG8_LDB(dst, b, h) do { _Pragma("unroll") for (int n = 0; n < 2; ++n) _Pragma("unroll") for (int k = 0; k < 2; ++k) dst[n][k] = *(const PG8_LAS bf16x8*)(lds + PG8_SB(b, h) + boff + n * 2048 + k * 1024); } while (0)
; #define PG8_MMA(ai, bj, At, Bt) do { __builtin_amdgcn_s_setprio(1); _Pragma("unroll") for (int m = 0; m < 4; ++m) _Pragma("unroll") for (int n = 0; n < 2; ++n) _Pragma("unroll") for (int k = 0; k < 2; ++k) \
;         acc[ai][bj][m][n] = __builtin_amdgcn_mfma_f32_16x16x32_bf16(Bt[n][k], At[m][k], acc[ai][bj][m][n], 0, 0, 0); __builtin_amdgcn_s_setprio(0); } while (0)
; #define PG8_WAIT_V(n) asm volatile("s_waitcnt vmcnt(" #n ")" ::: "memory")
; #define PG8_WAIT_L(n) asm volatile("s_waitcnt lgkmcnt(" #n ")" ::: "memory")
; #define PG8_BAR __builtin_amdgcn_s_barrier()
; #define PG8_SCHED __builtin_amdgcn_sched_barrier(0)
; template <class Epi, class Sched, bool ALIGN_EPI = false, bool SP2 = false>
; __device__ __forceinline__ void gemm_phase(PG8_LAS unsigned char* lds, const Gemm g, const Sched& S, const Epi& E) {
;     ...
;             PG8_LDB(B0, 1, 0); PG8_LDB(B1, 1, 1); PG8_SCHED; PG8_LDA(At, 1, 0); PG8_STAGE(PG8_SA(0, 1), a2 + hstep, voffA);
;             PG8_WAIT_V(8); PG8_WAIT_L(0); PG8_BAR; PG8_MMA(0, 0, At, B0); PG8_MMA(0, 1, At, B1); PG8_BAR; PG8_SCHED;
;             PG8_LDA(At, 1, 1); PG8_STAGE(PG8_SB(1, 0), b3, voffB); PG8_STAGE(PG8_SB(1, 1), b3 + hstep, voffB); PG8_STAGE(PG8_SA(1, 0), a3, voffA);
;             PG8_WAIT_V(8); PG8_WAIT_L(0); PG8_BAR; PG8_MMA(1, 0, At, B0); PG8_MMA(1, 1, At, B1); PG8_BAR; PG8_SCHED;
	s_add_i32 s70, 0, 0x18000
	v_add_u32_e32 v153, s70, v147
	s_add_i32 s71, 0, 0x1c000
	ds_read_b128 v[154:157], v153
	ds_read_b128 v[158:161], v153 offset:1024
	ds_read_b128 v[162:165], v153 offset:2048
	ds_read_b128 v[166:169], v153 offset:3072
	v_add_u32_e32 v153, s71, v147
	ds_read_b128 v[170:173], v153
	ds_read_b128 v[174:177], v153 offset:1024
	ds_read_b128 v[178:181], v153 offset:2048
	ds_read_b128 v[182:185], v153 offset:3072
	s_add_u32 s44, s44, 0x40000
	s_addc_u32 s45, s45, 0
	s_mov_b32 m0, s55
	ds_read_b128 v[186:189], v152 offset:32768
	ds_read_b128 v[190:193], v152 offset:33792
	ds_read_b128 v[198:201], v152 offset:34816
	ds_read_b128 v[202:205], v152 offset:35840
	ds_read_b128 v[206:209], v152 offset:36864
	ds_read_b128 v[210:213], v152 offset:37888
	ds_read_b128 v[214:217], v152 offset:38912
	ds_read_b128 v[218:221], v152 offset:39936
	global_load_lds_dwordx4 v134, s[44:45]
	s_mov_b32 m0, s56
	s_nop 0
	global_load_lds_dwordx4 v130, s[44:45]
	s_waitcnt vmcnt(8)
	s_waitcnt lgkmcnt(0)
	s_barrier
	v_mfma_f32_16x16x32_bf16 v[124:127], v[154:157], v[186:189], v[124:127]
	v_mfma_f32_16x16x32_bf16 v[116:119], v[162:165], v[186:189], v[116:119]
	v_mfma_f32_16x16x32_bf16 v[108:111], v[154:157], v[198:201], v[108:111]
	v_mfma_f32_16x16x32_bf16 v[100:103], v[162:165], v[198:201], v[100:103]
	v_mfma_f32_16x16x32_bf16 v[92:95], v[154:157], v[206:209], v[92:95]
	v_mfma_f32_16x16x32_bf16 v[84:87], v[162:165], v[206:209], v[84:87]
	v_mfma_f32_16x16x32_bf16 v[76:79], v[154:157], v[214:217], v[76:79]
	v_mfma_f32_16x16x32_bf16 v[68:71], v[162:165], v[214:217], v[68:71]
	v_mfma_f32_16x16x32_bf16 v[124:127], v[158:161], v[190:193], v[124:127]
	v_mfma_f32_16x16x32_bf16 v[116:119], v[166:169], v[190:193], v[116:119]
	v_mfma_f32_16x16x32_bf16 v[108:111], v[158:161], v[202:205], v[108:111]
	v_mfma_f32_16x16x32_bf16 v[100:103], v[166:169], v[202:205], v[100:103]
	v_mfma_f32_16x16x32_bf16 v[92:95], v[158:161], v[210:213], v[92:95]
	v_mfma_f32_16x16x32_bf16 v[84:87], v[166:169], v[210:213], v[84:87]
	v_mfma_f32_16x16x32_bf16 v[76:79], v[158:161], v[218:221], v[76:79]
	v_mfma_f32_16x16x32_bf16 v[68:71], v[166:169], v[218:221], v[68:71]
	v_mfma_f32_16x16x32_bf16 v[120:123], v[170:173], v[186:189], v[120:123]
	v_mfma_f32_16x16x32_bf16 v[112:115], v[178:181], v[186:189], v[112:115]
	v_mfma_f32_16x16x32_bf16 v[104:107], v[170:173], v[198:201], v[104:107]
	v_mfma_f32_16x16x32_bf16 v[96:99], v[178:181], v[198:201], v[96:99]
	v_mfma_f32_16x16x32_bf16 v[88:91], v[170:173], v[206:209], v[88:91]
	v_mfma_f32_16x16x32_bf16 v[80:83], v[178:181], v[206:209], v[80:83]
	v_mfma_f32_16x16x32_bf16 v[72:75], v[170:173], v[214:217], v[72:75]
	v_mfma_f32_16x16x32_bf16 v[64:67], v[178:181], v[214:217], v[64:67]
	v_mfma_f32_16x16x32_bf16 v[120:123], v[174:177], v[190:193], v[120:123]
	v_mfma_f32_16x16x32_bf16 v[112:115], v[182:185], v[190:193], v[112:115]
	v_mfma_f32_16x16x32_bf16 v[104:107], v[174:177], v[202:205], v[104:107]
	v_mfma_f32_16x16x32_bf16 v[96:99], v[182:185], v[202:205], v[96:99]
	v_mfma_f32_16x16x32_bf16 v[88:91], v[174:177], v[210:213], v[88:91]
	v_mfma_f32_16x16x32_bf16 v[80:83], v[182:185], v[210:213], v[80:83]
	v_mfma_f32_16x16x32_bf16 v[72:75], v[174:177], v[218:221], v[72:75]
	v_mfma_f32_16x16x32_bf16 v[64:67], v[182:185], v[218:221], v[64:67]
	s_barrier
	s_add_i32 s44, s70, s52
	s_mov_b32 m0, s44
	ds_read_b128 v[186:189], v152 offset:49152
	ds_read_b128 v[190:193], v152 offset:50176
	ds_read_b128 v[198:201], v152 offset:51200
	ds_read_b128 v[202:205], v152 offset:52224
	ds_read_b128 v[206:209], v152 offset:53248
	ds_read_b128 v[210:213], v152 offset:54272
	ds_read_b128 v[214:217], v152 offset:55296
	ds_read_b128 v[218:221], v152 offset:56320
	global_load_lds_dwordx4 v132, s[98:99]
	s_add_i32 m0, s44, 0x2000
	s_add_u32 s38, s38, 0x40080
	s_addc_u32 s39, s39, 0
	s_add_i32 s44, s71, s52
	global_load_lds_dwordx4 v128, s[98:99]
	s_mov_b32 m0, s44
	s_nop 0
	global_load_lds_dwordx4 v132, s[38:39]
	s_add_i32 m0, s44, 0x2000
	s_nop 0
	global_load_lds_dwordx4 v128, s[38:39]
	s_mov_b32 m0, s58
	s_nop 0
	global_load_lds_dwordx4 v134, s[100:101]
	s_mov_b32 m0, s59
	s_nop 0
	global_load_lds_dwordx4 v130, s[100:101]
	s_waitcnt vmcnt(8)
	s_waitcnt lgkmcnt(0)
	s_barrier
	v_mfma_f32_16x16x32_bf16 v[60:63], v[154:157], v[186:189], v[60:63]
	v_mfma_f32_16x16x32_bf16 v[52:55], v[162:165], v[186:189], v[52:55]
	v_mfma_f32_16x16x32_bf16 v[44:47], v[154:157], v[198:201], v[44:47]
	v_mfma_f32_16x16x32_bf16 v[36:39], v[162:165], v[198:201], v[36:39]
	v_mfma_f32_16x16x32_bf16 v[28:31], v[154:157], v[206:209], v[28:31]
	v_mfma_f32_16x16x32_bf16 v[20:23], v[162:165], v[206:209], v[20:23]
	v_mfma_f32_16x16x32_bf16 v[12:15], v[154:157], v[214:217], v[12:15]
	v_mfma_f32_16x16x32_bf16 v[4:7], v[162:165], v[214:217], v[4:7]
	v_mfma_f32_16x16x32_bf16 v[60:63], v[158:161], v[190:193], v[60:63]
	v_mfma_f32_16x16x32_bf16 v[52:55], v[166:169], v[190:193], v[52:55]
	v_mfma_f32_16x16x32_bf16 v[44:47], v[158:161], v[202:205], v[44:47]
	v_mfma_f32_16x16x32_bf16 v[36:39], v[166:169], v[202:205], v[36:39]
	v_mfma_f32_16x16x32_bf16 v[28:31], v[158:161], v[210:213], v[28:31]
	v_mfma_f32_16x16x32_bf16 v[20:23], v[166:169], v[210:213], v[20:23]
	v_mfma_f32_16x16x32_bf16 v[12:15], v[158:161], v[218:221], v[12:15]
	v_mfma_f32_16x16x32_bf16 v[4:7], v[166:169], v[218:221], v[4:7]
	v_mfma_f32_16x16x32_bf16 v[56:59], v[170:173], v[186:189], v[56:59]
	v_mfma_f32_16x16x32_bf16 v[48:51], v[178:181], v[186:189], v[48:51]
	v_mfma_f32_16x16x32_bf16 v[40:43], v[170:173], v[198:201], v[40:43]
	v_mfma_f32_16x16x32_bf16 v[32:35], v[178:181], v[198:201], v[32:35]
	v_mfma_f32_16x16x32_bf16 v[24:27], v[170:173], v[206:209], v[24:27]
	v_mfma_f32_16x16x32_bf16 v[16:19], v[178:181], v[206:209], v[16:19]
	v_mfma_f32_16x16x32_bf16 v[8:11], v[170:173], v[214:217], v[8:11]
	v_mfma_f32_16x16x32_bf16 v[0:3], v[178:181], v[214:217], v[0:3]
	v_mfma_f32_16x16x32_bf16 v[56:59], v[174:177], v[190:193], v[56:59]
	v_mfma_f32_16x16x32_bf16 v[48:51], v[182:185], v[190:193], v[48:51]
	v_mfma_f32_16x16x32_bf16 v[40:43], v[174:177], v[202:205], v[40:43]
	v_mfma_f32_16x16x32_bf16 v[32:35], v[182:185], v[202:205], v[32:35]
	v_mfma_f32_16x16x32_bf16 v[24:27], v[174:177], v[210:213], v[24:27]
	v_mfma_f32_16x16x32_bf16 v[16:19], v[182:185], v[210:213], v[16:19]
	v_mfma_f32_16x16x32_bf16 v[8:11], v[174:177], v[218:221], v[8:11]
	v_mfma_f32_16x16x32_bf16 v[0:3], v[182:185], v[218:221], v[0:3]
	s_barrier
	s_add_i32 s69, s69, 2
	s_add_u32 s20, s20, 0x100
	s_addc_u32 s21, s21, 0
	s_add_u32 s67, s67, 0x100
	s_addc_u32 s68, s68, 0
	s_cmp_gt_u32 s69, 13
	s_cbranch_scc0 .LBB0_810
	v_readlane_b32 s101, v249, 49
	s_nop 3
	s_cmp_eq_u32 s101, 0
	s_cbranch_scc1 .Ldw_done_1
	s_add_u32 s98, s28, 0x183500
	s_addc_u32 s99, s29, 0
	v_mov_b32_e32 v251, 0
	s_mov_b32 s100, 0

; __global__ void __launch_bounds__(NTHREADS, 2) mega_fwd(Args a) {
;     ...
;     if (IN(12)) {
;         { BUILD_RTAB(RT, T, 2048, false, 4) EpiBf E{QK, 2048, 4, C2, RT, KM}; run_gemm(lds, XB, (const bf16_t*)(ws + WS_WQK), T, 2048, D, E); }
.LBB0_1162:
	v_readlane_b32 s101, v249, 48
	s_nop 3
	s_cmp_lg_u32 s101, 0
	s_cselect_b32 s101, 4, 0
	v_writelane_b32 v249, s101, 49
	s_cmp_lt_i32 s30, 13
	s_cselect_b64 s[4:5], -1, 0
	s_and_b64 s[10:11], s[4:5], s[0:1]
	s_andn2_b64 vcc, exec, s[10:11]
	s_cbranch_vccnz .LBB0_1453
	s_ashr_i32 s3, s2, 31
	s_ashr_i32 s33, s22, 31
	s_mov_b32 s64, s22
	s_mov_b32 s65, -1
	s_mov_b32 s4, 16
	s_waitcnt lgkmcnt(0)
	v_mov_b64_e32 v[0:1], 0x3ff
	s_mov_b64 s[0:1], s[2:3]
	s_mov_b32 s67, -1
	s_mov_b32 s66, -1
	s_mov_b32 s8, -1
	s_branch .LBB0_1166

; #define PG8_STAGE(bufoff, gbase, voff) do { _Pragma("unroll") for (int _i = 0; _i < 2; ++_i) \
;         __builtin_amdgcn_global_load_lds((const unsigned*)((const char*)(gbase) + (voff)[_i]), (PG8_LAS unsigned*)(lds + (bufoff) + ldsw + _i * 8192), 16, 0, 0); } while (0)
; #define PG8_LDA(dst, b, h) do { _Pragma("unroll") for (int m = 0; m < 4; ++m) _Pragma("unroll") for (int k = 0; k < 2; ++k) dst[m][k] = *(const PG8_LAS bf16x8*)(lds + PG8_SA(b, h) + aoff + m * 2048 + k * 1024); } while (0)
; #define PG8_LDB(dst, b, h) do { _Pragma("unroll") for (int n = 0; n < 2; ++n) _Pragma("unroll") for (int k = 0; k < 2; ++k) dst[n][k] = *(const PG8_LAS bf16x8*)(lds + PG8_SB(b, h) + boff + n * 2048 + k * 1024); } while (0)
; #define PG8_MMA(ai, bj, At, Bt) do { __builtin_amdgcn_s_setprio(1); _Pragma("unroll") for (int m = 0; m < 4; ++m) _Pragma("unroll") for (int n = 0; n < 2; ++n) _Pragma("unroll") for (int k = 0; k < 2; ++k) \
;         acc[ai][bj][m][n] = __builtin_amdgcn_mfma_f32_16x16x32_bf16(Bt[n][k], At[m][k], acc[ai][bj][m][n], 0, 0, 0); __builtin_amdgcn_s_setprio(0); } while (0)
; #define PG8_WAIT_V(n) asm volatile("s_waitcnt vmcnt(" #n ")" ::: "memory")
; #define PG8_WAIT_L(n) asm volatile("s_waitcnt lgkmcnt(" #n ")" ::: "memory")
; template <class Epi, class Sched, bool ALIGN_EPI = false, bool SP2 = false>
; __device__ __forceinline__ void gemm_phase(PG8_LAS unsigned char* lds, const Gemm g, const Sched& S, const Epi& E) {
;     ...
;             const bool last = (t == nt - 2);
;             const char* a1 = cA + (size_t)(t + 1) * kstep;
;             const char* a2 = last ? nA : cA + (size_t)(t + 2) * kstep; const char* b2 = last ? nB : cB + (size_t)(t + 2) * kstep;
;             const char* a3 = a2 + kstep; const char* b3 = b2 + kstep;
;             if (last && has_next) S.a_ready(nxt);
;             if constexpr (SP2) {
;             PG8_LDB(B0, 0, 0); PG8_LDB(B1, 0, 1); PG8_SCHED; PG8_LDA(At, 0, 0); PG8_STAGE(PG8_SA(1, 1), a1 + hstep, voffA);
;             PG8_WAIT_V(8); PG8_WAIT_L(0); PG8_BAR; PG8_MMA(0, 0, At, B0); PG8_MMA(0, 1, At, B1); PG8_BAR; PG8_SCHED;
;             PG8_LDA(At, 0, 1); PG8_STAGE(PG8_SB(0, 0), b2, voffB); PG8_STAGE(PG8_SB(0, 1), b2 + hstep, voffB); PG8_STAGE(PG8_SA(0, 0), a2, voffA);
;             PG8_WAIT_V(8); PG8_WAIT_L(0); PG8_BAR; PG8_MMA(1, 0, At, B0); PG8_MMA(1, 1, At, B1); PG8_BAR; PG8_SCHED;
.LBB0_1200:
	ds_read_b128 v[140:143], v163
	ds_read_b128 v[168:171], v163 offset:1024
	ds_read_b128 v[172:175], v163 offset:2048
	ds_read_b128 v[176:179], v163 offset:3072
	ds_read_b128 v[180:183], v164
	ds_read_b128 v[184:187], v164 offset:1024
	ds_read_b128 v[188:191], v164 offset:2048
	ds_read_b128 v[192:195], v164 offset:3072
	s_add_u32 s34, s20, 0xfffc0080
	s_addc_u32 s35, s21, -1
	s_cmp_eq_u32 s88, 12
	s_cselect_b32 s63, s1, s35
	s_cselect_b32 s62, s57, s34
	s_cselect_b32 s35, s55, s87
	s_cselect_b32 s34, s85, s86
	s_add_i32 m0, s71, 0xc000
	ds_read_b128 v[198:201], v165
	ds_read_b128 v[202:205], v165 offset:1024
	ds_read_b128 v[206:209], v165 offset:2048
	ds_read_b128 v[210:213], v165 offset:3072
	ds_read_b128 v[214:217], v165 offset:4096
	ds_read_b128 v[218:221], v165 offset:5120
	ds_read_b128 v[222:225], v165 offset:6144
	ds_read_b128 v[226:229], v165 offset:7168
	global_load_lds_dwordx4 v132, s[20:21]
	s_add_i32 m0, s71, 0xe000
	s_nop 0
	global_load_lds_dwordx4 v134, s[20:21]
	s_waitcnt vmcnt(8)
	s_waitcnt lgkmcnt(0)
	s_barrier
	v_mfma_f32_16x16x32_bf16 v[124:127], v[140:143], v[198:201], v[124:127]
	v_mfma_f32_16x16x32_bf16 v[120:123], v[172:175], v[198:201], v[120:123]
	v_mfma_f32_16x16x32_bf16 v[108:111], v[140:143], v[206:209], v[108:111]
	v_mfma_f32_16x16x32_bf16 v[104:107], v[172:175], v[206:209], v[104:107]
	v_mfma_f32_16x16x32_bf16 v[92:95], v[140:143], v[214:217], v[92:95]
	v_mfma_f32_16x16x32_bf16 v[88:91], v[172:175], v[214:217], v[88:91]
	v_mfma_f32_16x16x32_bf16 v[76:79], v[140:143], v[222:225], v[76:79]
	v_mfma_f32_16x16x32_bf16 v[72:75], v[172:175], v[222:225], v[72:75]
	v_mfma_f32_16x16x32_bf16 v[124:127], v[168:171], v[202:205], v[124:127]
	v_mfma_f32_16x16x32_bf16 v[120:123], v[176:179], v[202:205], v[120:123]
	v_mfma_f32_16x16x32_bf16 v[108:111], v[168:171], v[210:213], v[108:111]
	v_mfma_f32_16x16x32_bf16 v[104:107], v[176:179], v[210:213], v[104:107]
	v_mfma_f32_16x16x32_bf16 v[92:95], v[168:171], v[218:221], v[92:95]
	v_mfma_f32_16x16x32_bf16 v[88:91], v[176:179], v[218:221], v[88:91]
	v_mfma_f32_16x16x32_bf16 v[76:79], v[168:171], v[226:229], v[76:79]
	v_mfma_f32_16x16x32_bf16 v[72:75], v[176:179], v[226:229], v[72:75]
	v_mfma_f32_16x16x32_bf16 v[116:119], v[180:183], v[198:201], v[116:119]
	v_mfma_f32_16x16x32_bf16 v[112:115], v[188:191], v[198:201], v[112:115]
	v_mfma_f32_16x16x32_bf16 v[100:103], v[180:183], v[206:209], v[100:103]
	v_mfma_f32_16x16x32_bf16 v[96:99], v[188:191], v[206:209], v[96:99]
	v_mfma_f32_16x16x32_bf16 v[84:87], v[180:183], v[214:217], v[84:87]
	v_mfma_f32_16x16x32_bf16 v[80:83], v[188:191], v[214:217], v[80:83]
	v_mfma_f32_16x16x32_bf16 v[68:71], v[180:183], v[222:225], v[68:71]
	v_mfma_f32_16x16x32_bf16 v[64:67], v[188:191], v[222:225], v[64:67]
	v_mfma_f32_16x16x32_bf16 v[116:119], v[184:187], v[202:205], v[116:119]
	v_mfma_f32_16x16x32_bf16 v[112:115], v[192:195], v[202:205], v[112:115]
	v_mfma_f32_16x16x32_bf16 v[100:103], v[184:187], v[210:213], v[100:103]
	v_mfma_f32_16x16x32_bf16 v[96:99], v[192:195], v[210:213], v[96:99]
	v_mfma_f32_16x16x32_bf16 v[84:87], v[184:187], v[218:221], v[84:87]
	v_mfma_f32_16x16x32_bf16 v[80:83], v[192:195], v[218:221], v[80:83]
	v_mfma_f32_16x16x32_bf16 v[68:71], v[184:187], v[226:229], v[68:71]
	v_mfma_f32_16x16x32_bf16 v[64:67], v[192:195], v[226:229], v[64:67]
	s_barrier
	s_add_i32 s89, s77, s70
	s_add_u32 s98, s34, s18
	s_addc_u32 s99, s35, s19
	s_add_u32 s100, s62, s18
	s_addc_u32 s101, s63, s19
	s_mov_b32 m0, s89
	ds_read_b128 v[198:201], v165 offset:16384
	ds_read_b128 v[202:205], v165 offset:17408
	ds_read_b128 v[206:209], v165 offset:18432
	ds_read_b128 v[210:213], v165 offset:19456
	ds_read_b128 v[214:217], v165 offset:20480
	ds_read_b128 v[218:221], v165 offset:21504
	ds_read_b128 v[222:225], v165 offset:22528
	ds_read_b128 v[226:229], v165 offset:23552
	global_load_lds_dwordx4 v146, s[34:35]
	s_add_i32 m0, s89, 0x2000
	s_add_u32 s90, s34, 0x40000
	s_addc_u32 s91, s35, 0
	s_add_i32 s89, s78, s70
	global_load_lds_dwordx4 v150, s[34:35]
	s_mov_b32 m0, s89
	s_nop 0
	global_load_lds_dwordx4 v146, s[90:91]
	s_add_i32 m0, s89, 0x2000
	s_nop 0
	global_load_lds_dwordx4 v150, s[90:91]
	s_mov_b32 m0, s71
	s_nop 0
	global_load_lds_dwordx4 v144, s[62:63]
	s_mov_b32 m0, s72
	s_nop 0
	global_load_lds_dwordx4 v148, s[62:63]
	s_waitcnt vmcnt(8)
	s_waitcnt lgkmcnt(0)
	s_barrier
	v_mfma_f32_16x16x32_bf16 v[60:63], v[140:143], v[198:201], v[60:63]
	v_mfma_f32_16x16x32_bf16 v[56:59], v[172:175], v[198:201], v[56:59]
	v_mfma_f32_16x16x32_bf16 v[48:51], v[140:143], v[206:209], v[48:51]
	v_mfma_f32_16x16x32_bf16 v[40:43], v[172:175], v[206:209], v[40:43]
	v_mfma_f32_16x16x32_bf16 v[32:35], v[140:143], v[214:217], v[32:35]
	v_mfma_f32_16x16x32_bf16 v[24:27], v[172:175], v[214:217], v[24:27]
	v_mfma_f32_16x16x32_bf16 v[16:19], v[140:143], v[222:225], v[16:19]
	v_mfma_f32_16x16x32_bf16 v[8:11], v[172:175], v[222:225], v[8:11]
	v_mfma_f32_16x16x32_bf16 v[60:63], v[168:171], v[202:205], v[60:63]
	v_mfma_f32_16x16x32_bf16 v[56:59], v[176:179], v[202:205], v[56:59]
	v_mfma_f32_16x16x32_bf16 v[48:51], v[168:171], v[210:213], v[48:51]
	v_mfma_f32_16x16x32_bf16 v[40:43], v[176:179], v[210:213], v[40:43]
	v_mfma_f32_16x16x32_bf16 v[32:35], v[168:171], v[218:221], v[32:35]
	v_mfma_f32_16x16x32_bf16 v[24:27], v[176:179], v[218:221], v[24:27]
	v_mfma_f32_16x16x32_bf16 v[16:19], v[168:171], v[226:229], v[16:19]
	v_mfma_f32_16x16x32_bf16 v[8:11], v[176:179], v[226:229], v[8:11]
	v_mfma_f32_16x16x32_bf16 v[52:55], v[180:183], v[198:201], v[52:55]
	v_mfma_f32_16x16x32_bf16 v[44:47], v[188:191], v[198:201], v[44:47]
	v_mfma_f32_16x16x32_bf16 v[36:39], v[180:183], v[206:209], v[36:39]
	v_mfma_f32_16x16x32_bf16 v[28:31], v[188:191], v[206:209], v[28:31]
	v_mfma_f32_16x16x32_bf16 v[20:23], v[180:183], v[214:217], v[20:23]
	v_mfma_f32_16x16x32_bf16 v[12:15], v[188:191], v[214:217], v[12:15]
	v_mfma_f32_16x16x32_bf16 v[4:7], v[180:183], v[222:225], v[4:7]
	v_mfma_f32_16x16x32_bf16 v[0:3], v[188:191], v[222:225], v[0:3]
	v_mfma_f32_16x16x32_bf16 v[52:55], v[184:187], v[202:205], v[52:55]
	v_mfma_f32_16x16x32_bf16 v[44:47], v[192:195], v[202:205], v[44:47]
	v_mfma_f32_16x16x32_bf16 v[36:39], v[184:187], v[210:213], v[36:39]
	v_mfma_f32_16x16x32_bf16 v[28:31], v[192:195], v[210:213], v[28:31]
	v_mfma_f32_16x16x32_bf16 v[20:23], v[184:187], v[218:221], v[20:23]
	v_mfma_f32_16x16x32_bf16 v[12:15], v[192:195], v[218:221], v[12:15]
	v_mfma_f32_16x16x32_bf16 v[4:7], v[184:187], v[226:229], v[4:7]
	v_mfma_f32_16x16x32_bf16 v[0:3], v[192:195], v[226:229], v[0:3]
	s_barrier
; #define PG8_STAGE(bufoff, gbase, voff) do { _Pragma("unroll") for (int _i = 0; _i < 2; ++_i) \
;         __builtin_amdgcn_global_load_lds((const unsigned*)((const char*)(gbase) + (voff)[_i]), (PG8_LAS unsigned*)(lds + (bufoff) + ldsw + _i * 8192), 16, 0, 0); } while (0)
; #define PG8_LDA(dst, b, h) do { _Pragma("unroll") for (int m = 0; m < 4; ++m) _Pragma("unroll") for (int k = 0; k < 2; ++k) dst[m][k] = *(const PG8_LAS bf16x8*)(lds + PG8_SA(b, h) + aoff + m * 2048 + k * 1024); } while (0)
; #define PG8_LDB(dst, b, h) do { _Pragma("unroll") for (int n = 0; n < 2; ++n) _Pragma("unroll") for (int k = 0; k < 2; ++k) dst[n][k] = *(const PG8_LAS bf16x8*)(lds + PG8_SB(b, h) + boff + n * 2048 + k * 1024); } while (0)
; #define PG8_MMA(ai, bj, At, Bt) do { __builtin_amdgcn_s_setprio(1); _Pragma("unroll") for (int m = 0; m < 4; ++m) _Pragma("unroll") for (int n = 0; n < 2; ++n) _Pragma("unroll") for (int k = 0; k < 2; ++k) \
;         acc[ai][bj][m][n] = __builtin_amdgcn_mfma_f32_16x16x32_bf16(Bt[n][k], At[m][k], acc[ai][bj][m][n], 0, 0, 0); __builtin_amdgcn_s_setprio(0); } while (0)
; #define PG8_WAIT_V(n) asm volatile("s_waitcnt vmcnt(" #n ")" ::: "memory")
; #define PG8_WAIT_L(n) asm volatile("s_waitcnt lgkmcnt(" #n ")" ::: "memory")
; #define PG8_BAR __builtin_amdgcn_s_barrier()
; #define PG8_SCHED __builtin_amdgcn_sched_barrier(0)
; template <class Epi, class Sched, bool ALIGN_EPI = false, bool SP2 = false>
; __device__ __forceinline__ void gemm_phase(PG8_LAS unsigned char* lds, const Gemm g, const Sched& S, const Epi& E) {
;     ...
;             PG8_LDB(B0, 1, 0); PG8_LDB(B1, 1, 1); PG8_SCHED; PG8_LDA(At, 1, 0); PG8_STAGE(PG8_SA(0, 1), a2 + hstep, voffA);
;             PG8_WAIT_V(8); PG8_WAIT_L(0); PG8_BAR; PG8_MMA(0, 0, At, B0); PG8_MMA(0, 1, At, B1); PG8_BAR; PG8_SCHED;
;             PG8_LDA(At, 1, 1); PG8_STAGE(PG8_SB(1, 0), b3, voffB); PG8_STAGE(PG8_SB(1, 1), b3 + hstep, voffB); PG8_STAGE(PG8_SA(1, 0), a3, voffA);
;             PG8_WAIT_V(8); PG8_WAIT_L(0); PG8_BAR; PG8_MMA(1, 0, At, B0); PG8_MMA(1, 1, At, B1); PG8_BAR; PG8_SCHED;
	s_add_i32 s89, 0, 0x18000
	v_add_u32_e32 v128, s89, v161
	s_add_i32 s90, 0, 0x1c000
	ds_read_b128 v[140:143], v128
	ds_read_b128 v[168:171], v128 offset:1024
	ds_read_b128 v[172:175], v128 offset:2048
	ds_read_b128 v[176:179], v128 offset:3072
	v_add_u32_e32 v128, s90, v161
	ds_read_b128 v[180:183], v128
	ds_read_b128 v[184:187], v128 offset:1024
	ds_read_b128 v[188:191], v128 offset:2048
	ds_read_b128 v[192:195], v128 offset:3072
	s_add_u32 s62, s62, 0x40000
	s_addc_u32 s63, s63, 0
	s_mov_b32 m0, s73
	ds_read_b128 v[198:201], v165 offset:32768
	ds_read_b128 v[202:205], v165 offset:33792
	ds_read_b128 v[206:209], v165 offset:34816
	ds_read_b128 v[210:213], v165 offset:35840
	ds_read_b128 v[214:217], v165 offset:36864
	ds_read_b128 v[218:221], v165 offset:37888
	ds_read_b128 v[222:225], v165 offset:38912
	ds_read_b128 v[226:229], v165 offset:39936
	global_load_lds_dwordx4 v144, s[62:63]
	s_mov_b32 m0, s74
	s_nop 0
	global_load_lds_dwordx4 v148, s[62:63]
	s_waitcnt vmcnt(8)
	s_waitcnt lgkmcnt(0)
	s_barrier
	v_mfma_f32_16x16x32_bf16 v[124:127], v[140:143], v[198:201], v[124:127]
	v_mfma_f32_16x16x32_bf16 v[120:123], v[172:175], v[198:201], v[120:123]
	v_mfma_f32_16x16x32_bf16 v[108:111], v[140:143], v[206:209], v[108:111]
	v_mfma_f32_16x16x32_bf16 v[104:107], v[172:175], v[206:209], v[104:107]
	v_mfma_f32_16x16x32_bf16 v[92:95], v[140:143], v[214:217], v[92:95]
	v_mfma_f32_16x16x32_bf16 v[88:91], v[172:175], v[214:217], v[88:91]
	v_mfma_f32_16x16x32_bf16 v[76:79], v[140:143], v[222:225], v[76:79]
	v_mfma_f32_16x16x32_bf16 v[72:75], v[172:175], v[222:225], v[72:75]
	v_mfma_f32_16x16x32_bf16 v[124:127], v[168:171], v[202:205], v[124:127]
	v_mfma_f32_16x16x32_bf16 v[120:123], v[176:179], v[202:205], v[120:123]
	v_mfma_f32_16x16x32_bf16 v[108:111], v[168:171], v[210:213], v[108:111]
	v_mfma_f32_16x16x32_bf16 v[104:107], v[176:179], v[210:213], v[104:107]
	v_mfma_f32_16x16x32_bf16 v[92:95], v[168:171], v[218:221], v[92:95]
	v_mfma_f32_16x16x32_bf16 v[88:91], v[176:179], v[218:221], v[88:91]
	v_mfma_f32_16x16x32_bf16 v[76:79], v[168:171], v[226:229], v[76:79]
	v_mfma_f32_16x16x32_bf16 v[72:75], v[176:179], v[226:229], v[72:75]
	v_mfma_f32_16x16x32_bf16 v[116:119], v[180:183], v[198:201], v[116:119]
	v_mfma_f32_16x16x32_bf16 v[112:115], v[188:191], v[198:201], v[112:115]
	v_mfma_f32_16x16x32_bf16 v[100:103], v[180:183], v[206:209], v[100:103]
	v_mfma_f32_16x16x32_bf16 v[96:99], v[188:191], v[206:209], v[96:99]
	v_mfma_f32_16x16x32_bf16 v[84:87], v[180:183], v[214:217], v[84:87]
	v_mfma_f32_16x16x32_bf16 v[80:83], v[188:191], v[214:217], v[80:83]
	v_mfma_f32_16x16x32_bf16 v[68:71], v[180:183], v[222:225], v[68:71]
	v_mfma_f32_16x16x32_bf16 v[64:67], v[188:191], v[222:225], v[64:67]
	v_mfma_f32_16x16x32_bf16 v[116:119], v[184:187], v[202:205], v[116:119]
	v_mfma_f32_16x16x32_bf16 v[112:115], v[192:195], v[202:205], v[112:115]
	v_mfma_f32_16x16x32_bf16 v[100:103], v[184:187], v[210:213], v[100:103]
	v_mfma_f32_16x16x32_bf16 v[96:99], v[192:195], v[210:213], v[96:99]
	v_mfma_f32_16x16x32_bf16 v[84:87], v[184:187], v[218:221], v[84:87]
	v_mfma_f32_16x16x32_bf16 v[80:83], v[192:195], v[218:221], v[80:83]
	v_mfma_f32_16x16x32_bf16 v[68:71], v[184:187], v[226:229], v[68:71]
	v_mfma_f32_16x16x32_bf16 v[64:67], v[192:195], v[226:229], v[64:67]
	s_barrier
	s_add_i32 s62, s89, s70
	s_mov_b32 m0, s62
	ds_read_b128 v[198:201], v165 offset:49152
	ds_read_b128 v[202:205], v165 offset:50176
	ds_read_b128 v[206:209], v165 offset:51200
	ds_read_b128 v[210:213], v165 offset:52224
	ds_read_b128 v[214:217], v165 offset:53248
	ds_read_b128 v[218:221], v165 offset:54272
	ds_read_b128 v[222:225], v165 offset:55296
	ds_read_b128 v[226:229], v165 offset:56320
	global_load_lds_dwordx4 v146, s[98:99]
	s_add_i32 m0, s62, 0x2000
	s_add_u32 s34, s34, 0x40080
	s_addc_u32 s35, s35, 0
	s_add_i32 s62, s90, s70
	global_load_lds_dwordx4 v150, s[98:99]
	s_mov_b32 m0, s62
	s_nop 0
	global_load_lds_dwordx4 v146, s[34:35]
	s_add_i32 m0, s62, 0x2000
	s_nop 0
	global_load_lds_dwordx4 v150, s[34:35]
	s_mov_b32 m0, s75
	s_nop 0
	global_load_lds_dwordx4 v144, s[100:101]
	s_mov_b32 m0, s76
	s_nop 0
	global_load_lds_dwordx4 v148, s[100:101]
	s_waitcnt vmcnt(8)
	s_waitcnt lgkmcnt(0)
	s_barrier
	v_mfma_f32_16x16x32_bf16 v[60:63], v[140:143], v[198:201], v[60:63]
	v_mfma_f32_16x16x32_bf16 v[56:59], v[172:175], v[198:201], v[56:59]
	v_mfma_f32_16x16x32_bf16 v[48:51], v[140:143], v[206:209], v[48:51]
	v_mfma_f32_16x16x32_bf16 v[40:43], v[172:175], v[206:209], v[40:43]
	v_mfma_f32_16x16x32_bf16 v[32:35], v[140:143], v[214:217], v[32:35]
	v_mfma_f32_16x16x32_bf16 v[24:27], v[172:175], v[214:217], v[24:27]
	v_mfma_f32_16x16x32_bf16 v[16:19], v[140:143], v[222:225], v[16:19]
	v_mfma_f32_16x16x32_bf16 v[8:11], v[172:175], v[222:225], v[8:11]
	v_mfma_f32_16x16x32_bf16 v[60:63], v[168:171], v[202:205], v[60:63]
	v_mfma_f32_16x16x32_bf16 v[56:59], v[176:179], v[202:205], v[56:59]
	v_mfma_f32_16x16x32_bf16 v[48:51], v[168:171], v[210:213], v[48:51]
	v_mfma_f32_16x16x32_bf16 v[40:43], v[176:179], v[210:213], v[40:43]
	v_mfma_f32_16x16x32_bf16 v[32:35], v[168:171], v[218:221], v[32:35]
	v_mfma_f32_16x16x32_bf16 v[24:27], v[176:179], v[218:221], v[24:27]
	v_mfma_f32_16x16x32_bf16 v[16:19], v[168:171], v[226:229], v[16:19]
	v_mfma_f32_16x16x32_bf16 v[8:11], v[176:179], v[226:229], v[8:11]
	v_mfma_f32_16x16x32_bf16 v[52:55], v[180:183], v[198:201], v[52:55]
	v_mfma_f32_16x16x32_bf16 v[44:47], v[188:191], v[198:201], v[44:47]
	v_mfma_f32_16x16x32_bf16 v[36:39], v[180:183], v[206:209], v[36:39]
	v_mfma_f32_16x16x32_bf16 v[28:31], v[188:191], v[206:209], v[28:31]
	v_mfma_f32_16x16x32_bf16 v[20:23], v[180:183], v[214:217], v[20:23]
	v_mfma_f32_16x16x32_bf16 v[12:15], v[188:191], v[214:217], v[12:15]
	v_mfma_f32_16x16x32_bf16 v[4:7], v[180:183], v[222:225], v[4:7]
	v_mfma_f32_16x16x32_bf16 v[0:3], v[188:191], v[222:225], v[0:3]
	v_mfma_f32_16x16x32_bf16 v[52:55], v[184:187], v[202:205], v[52:55]
	v_mfma_f32_16x16x32_bf16 v[44:47], v[192:195], v[202:205], v[44:47]
	v_mfma_f32_16x16x32_bf16 v[36:39], v[184:187], v[210:213], v[36:39]
	v_mfma_f32_16x16x32_bf16 v[28:31], v[192:195], v[210:213], v[28:31]
	v_mfma_f32_16x16x32_bf16 v[20:23], v[184:187], v[218:221], v[20:23]
	v_mfma_f32_16x16x32_bf16 v[12:15], v[192:195], v[218:221], v[12:15]
	v_mfma_f32_16x16x32_bf16 v[4:7], v[184:187], v[226:229], v[4:7]
	v_mfma_f32_16x16x32_bf16 v[0:3], v[192:195], v[226:229], v[0:3]
	s_barrier
	s_add_i32 s88, s88, 2
	s_add_u32 s20, s20, 0x100
	s_addc_u32 s21, s21, 0
	s_add_u32 s86, s86, 0x100
	s_addc_u32 s87, s87, 0
	s_cmp_gt_u32 s88, 13
	s_cbranch_scc0 .LBB0_1200
	v_readlane_b32 s101, v249, 49
	s_nop 3
	s_cmp_eq_u32 s101, 0
	s_cbranch_scc1 .Ldw_done_2
	s_add_u32 s98, s28, 0x183500
	s_addc_u32 s99, s29, 0
	v_mov_b32_e32 v251, 0
	s_mov_b32 s100, 0

; #define PG8_BAR __builtin_amdgcn_s_barrier()
; template <class Epi, class Sched, bool ALIGN_EPI = false, bool SP2 = false>
; __device__ __forceinline__ void gemm_phase(PG8_LAS unsigned char* lds, const Gemm g, const Sched& S, const Epi& E) {
;     ...
;         if constexpr (ALIGN_EPI) { if (wr == 0) PG8_BAR; }
.Ldw_done_2:
	s_and_b64 vcc, exec, s[38:39]
	s_cbranch_vccz .LBB0_1203
	s_barrier

; #define PG8_LAS __attribute__((address_space(3)))
; #define PG8_STAGE(bufoff, gbase, voff) do { _Pragma("unroll") for (int _i = 0; _i < 2; ++_i) \
;         __builtin_amdgcn_global_load_lds((const unsigned*)((const char*)(gbase) + (voff)[_i]), (PG8_LAS unsigned*)(lds + (bufoff) + ldsw + _i * 8192), 16, 0, 0); } while (0)
;     __host__ __device__ bool next(int i, Unit& u) const {
;         const long L = (long)i * G + c; if (L >= nwg) return false;
;         int wgid = (int)L; { const int q = nwg / NXCD, r = nwg % NXCD, xcd = wgid % NXCD, off = wgid / NXCD; wgid = (xcd < r ? xcd * (q + 1) : r * (q + 1) + (xcd - r) * q) + off; }
;         const int nig = WGM * nN, gid = wgid / nig, fm = gid * WGM, gsz = (nM - fm) < WGM ? (nM - fm) : WGM;
;         u.pm = fm + ((wgid % nig) % gsz); u.pn = (wgid % nig) / gsz; return true;
;     }
; __device__ __forceinline__ unsigned cvt_pk_bf16(float lo, float hi) { unsigned r; asm volatile("v_cvt_pk_bf16_f32 %0, %1, %2" : "=v"(r) : "v"(lo), "v"(hi)); return r; }
; template <class Epi, class Sched, bool ALIGN_EPI = false, bool SP2 = false>
; __device__ __forceinline__ void gemm_phase(PG8_LAS unsigned char* lds, const Gemm g, const Sched& S, const Epi& E) {
;     const int tid = threadIdx.x, wid = __builtin_amdgcn_readfirstlane(tid >> 6), lane = tid & 63, wr = wid >> 2, wc = wid & 3, fr = lane & 15, fq = lane >> 4;
;     const int K = g.K, nt = K / BK;
;     unsigned voffA[2], voffB[2];
; #pragma unroll
;     for (int i = 0; i < 2; ++i) { int R, C; stage_rc(tid * 16 + i * 8192, R, C); const int Rb = Epi::PERM ? ((R & ~31) + perm32(R & 31)) : R;
;         voffA[i] = (unsigned)(R * K + C) * 2u; voffB[i] = (unsigned)(Rb * K + C) * 2u; }
;     ...
;     const char* cA = (const char*)g.A + (size_t)cur.pm * tstep; const char* cB = (const char*)g.Bt + (size_t)cur.pn * tstep;
;     S.a_ready(cur);
;     if constexpr (SP2) {
;         PG8_STAGE(PG8_SB(0, 0), cB, voffB); PG8_STAGE(PG8_SB(0, 1), cB + hstep, voffB); PG8_STAGE(PG8_SA(0, 0), cA, voffA); PG8_STAGE(PG8_SA(0, 1), cA + hstep, voffA);
.LBB0_1712:
	v_readlane_b32 s101, v249, 48
	s_nop 3
	s_cmp_lg_u32 s101, 0
	s_cselect_b32 s101, 5, 0
	v_writelane_b32 v249, s101, 49
	s_cmp_lt_i32 s30, 17
	s_cselect_b64 s[0:1], -1, 0
	s_and_b64 s[6:7], s[0:1], s[4:5]
	s_andn2_b64 vcc, exec, s[6:7]
	s_cbranch_vccnz .LBB0_1747
	s_ashr_i32 s3, s2, 31
	s_cmpk_lt_i32 s2, 0xb00
	s_cbranch_scc0 .Lpro_skip_4
	v_readfirstlane_b32 s5, v197
	s_nop 3
	v_lshrrev_b32_e32 v0, 5, v197
	v_lshrrev_b32_e32 v2, 1, v197
	v_and_b32_e32 v0, 4, v0
	v_bfe_u32 v1, v197, 2, 2
	v_and_b32_e32 v11, 24, v2
	v_or3_b32 v0, v0, v1, v11
	v_lshlrev_b32_e32 v1, 4, v197
	v_add_u32_e32 v8, 0x2000, v1
	v_lshrrev_b32_e32 v2, 7, v8
	s_movk_i32 s0, 0xe0
	v_and_b32_e32 v4, 32, v197
	v_and_or_b32 v3, v2, s0, v0
	v_bitop3_b32 v9, v1, v4, 48 bitop3:0x6c
	v_and_b32_e32 v10, 64, v197
	v_bfe_u32 v12, v197, 2, 4
	s_movk_i32 s0, 0xf0
	v_or_b32_e32 v1, v9, v10
	v_and_or_b32 v2, v2, s0, v12
	v_lshl_or_b32 v130, v2, 11, v1
	v_lshrrev_b32_e32 v2, 3, v197
	s_movk_i32 s0, 0x60
	s_add_u32 s48, s28, 0x2900000
	v_and_or_b32 v0, v2, s0, v0
	s_movk_i32 s0, 0x70
	s_addc_u32 s49, s29, 0
	v_lshl_or_b32 v132, v0, 11, v1
	v_and_or_b32 v0, v2, s0, v12
	s_lshr_b32 s0, s3, 29
	s_add_i32 s0, s2, s0
	s_lshr_b32 s8, s5, 6
	s_ashr_i32 s1, s0, 3
	s_and_b32 s0, s0, -8
	s_lshr_b32 s12, s5, 8
	s_lshl_b32 s50, s8, 10
	s_sub_i32 s0, s2, s0
	s_cmp_lt_i32 s0, 0
	s_movk_i32 s51, 0x161
	s_cselect_b32 s4, s51, 0x160
	s_mul_i32 s0, s4, s0
	s_add_i32 s0, s0, s1
	s_mul_hi_i32 s1, s0, 0x2e8ba2e9
	s_lshr_b32 s4, s1, 31
	s_ashr_i32 s1, s1, 5
	s_add_i32 s1, s1, s4
	s_lshl_b32 s9, s1, 3
	s_mulk_i32 s1, 0xb0
	s_sub_i32 s0, s0, s1
	s_sext_i32_i16 s1, s0
	s_bfe_u32 s1, s1, 0x3001c
	s_add_i32 s1, s0, s1
	s_sext_i32_i16 s4, s1
	s_and_b32 s1, s1, 0xfff8
	s_sub_i32 s0, s0, s1
	s_sext_i32_i16 s0, s0
	s_lshr_b32 s4, s4, 3
	s_add_i32 s34, s9, s0
	s_ashr_i32 s35, s34, 31
	s_bfe_i64 s[10:11], s[4:5], 0x100000
	s_lshl_b64 s[0:1], s[34:35], 19
	s_lshl_b64 s[10:11], s[10:11], 19
	s_add_u32 s38, s48, s10
	s_addc_u32 s39, s49, s11
	s_add_i32 s35, s50, 0
	s_add_i32 m0, s35, 0x10000
	v_lshl_or_b32 v128, v3, 11, v1
	global_load_lds_dwordx4 v132, s[38:39]
	s_add_i32 m0, s35, 0x12000
	s_add_u32 s10, s38, 0x40000
	global_load_lds_dwordx4 v128, s[38:39]
	s_addc_u32 s11, s39, 0
	s_add_i32 m0, s35, 0x14000
	v_lshl_or_b32 v134, v0, 11, v1
	global_load_lds_dwordx4 v132, s[10:11]
	s_add_i32 m0, s35, 0x16000
	s_add_u32 s20, s36, s0
	s_addc_u32 s21, s37, s1
	s_add_i32 s52, s35, 0x2000
	global_load_lds_dwordx4 v128, s[10:11]
	s_mov_b32 m0, s35
	s_add_u32 s0, s20, 0x40000
	global_load_lds_dwordx4 v134, s[20:21]
	s_mov_b32 m0, s52
	s_addc_u32 s1, s21, 0
	s_add_i32 s53, s35, 0x4000
	global_load_lds_dwordx4 v130, s[20:21]
	s_mov_b32 m0, s53
	s_add_i32 s54, s35, 0x6000
	global_load_lds_dwordx4 v134, s[0:1]
	s_mov_b32 m0, s54
	v_mov_b32_e32 v133, 0
	global_load_lds_dwordx4 v130, s[0:1]
	s_mov_b32 s98, s12
	s_mov_b32 s99, s4
	s_mov_b32 s100, s8
	v_mov_b32_e32 v240, v10
	v_mov_b32_e32 v241, v11
	v_mov_b32_e32 v242, v12
	v_mov_b32_e32 v243, v8
	v_mov_b32_e32 v244, v9

; #define PG8_STAGE(bufoff, gbase, voff) do { _Pragma("unroll") for (int _i = 0; _i < 2; ++_i) \
;         __builtin_amdgcn_global_load_lds((const unsigned*)((const char*)(gbase) + (voff)[_i]), (PG8_LAS unsigned*)(lds + (bufoff) + ldsw + _i * 8192), 16, 0, 0); } while (0)
; #define PG8_LDA(dst, b, h) do { _Pragma("unroll") for (int m = 0; m < 4; ++m) _Pragma("unroll") for (int k = 0; k < 2; ++k) dst[m][k] = *(const PG8_LAS bf16x8*)(lds + PG8_SA(b, h) + aoff + m * 2048 + k * 1024); } while (0)
; #define PG8_LDB(dst, b, h) do { _Pragma("unroll") for (int n = 0; n < 2; ++n) _Pragma("unroll") for (int k = 0; k < 2; ++k) dst[n][k] = *(const PG8_LAS bf16x8*)(lds + PG8_SB(b, h) + boff + n * 2048 + k * 1024); } while (0)
; #define PG8_MMA(ai, bj, At, Bt) do { __builtin_amdgcn_s_setprio(1); _Pragma("unroll") for (int m = 0; m < 4; ++m) _Pragma("unroll") for (int n = 0; n < 2; ++n) _Pragma("unroll") for (int k = 0; k < 2; ++k) \
;         acc[ai][bj][m][n] = __builtin_amdgcn_mfma_f32_16x16x32_bf16(Bt[n][k], At[m][k], acc[ai][bj][m][n], 0, 0, 0); __builtin_amdgcn_s_setprio(0); } while (0)
; #define PG8_WAIT_V(n) asm volatile("s_waitcnt vmcnt(" #n ")" ::: "memory")
; #define PG8_WAIT_L(n) asm volatile("s_waitcnt lgkmcnt(" #n ")" ::: "memory")
; template <class Epi, class Sched, bool ALIGN_EPI = false, bool SP2 = false>
; __device__ __forceinline__ void gemm_phase(PG8_LAS unsigned char* lds, const Gemm g, const Sched& S, const Epi& E) {
;     ...
;             const bool last = (t == nt - 2);
;             const char* a1 = cA + (size_t)(t + 1) * kstep;
;             const char* a2 = last ? nA : cA + (size_t)(t + 2) * kstep; const char* b2 = last ? nB : cB + (size_t)(t + 2) * kstep;
;             const char* a3 = a2 + kstep; const char* b3 = b2 + kstep;
;             if (last && has_next) S.a_ready(nxt);
;             if constexpr (SP2) {
;             PG8_LDB(B0, 0, 0); PG8_LDB(B1, 0, 1); PG8_SCHED; PG8_LDA(At, 0, 0); PG8_STAGE(PG8_SA(1, 1), a1 + hstep, voffA);
;             PG8_WAIT_V(8); PG8_WAIT_L(0); PG8_BAR; PG8_MMA(0, 0, At, B0); PG8_MMA(0, 1, At, B1); PG8_BAR; PG8_SCHED;
;             PG8_LDA(At, 0, 1); PG8_STAGE(PG8_SB(0, 0), b2, voffB); PG8_STAGE(PG8_SB(0, 1), b2 + hstep, voffB); PG8_STAGE(PG8_SA(0, 0), a2, voffA);
;             PG8_WAIT_V(8); PG8_WAIT_L(0); PG8_BAR; PG8_MMA(1, 0, At, B0); PG8_MMA(1, 1, At, B1); PG8_BAR; PG8_SCHED;
.LBB0_1740:
	ds_read_b128 v[154:157], v150
	ds_read_b128 v[158:161], v150 offset:1024
	ds_read_b128 v[162:165], v150 offset:2048
	ds_read_b128 v[166:169], v150 offset:3072
	ds_read_b128 v[170:173], v151
	ds_read_b128 v[174:177], v151 offset:1024
	ds_read_b128 v[178:181], v151 offset:2048
	ds_read_b128 v[182:185], v151 offset:3072
	s_add_u32 s38, s20, 0xfffc0080
	s_addc_u32 s39, s21, -1
	s_cmp_eq_u32 s67, 12
	s_cselect_b32 s43, s15, s39
	s_cselect_b32 s42, s63, s38
	s_cselect_b32 s39, s13, s66
	s_cselect_b32 s38, s64, s65
	s_add_i32 m0, s35, 0xc000
	ds_read_b128 v[186:189], v152
	ds_read_b128 v[190:193], v152 offset:1024
	ds_read_b128 v[198:201], v152 offset:2048
	ds_read_b128 v[202:205], v152 offset:3072
	ds_read_b128 v[206:209], v152 offset:4096
	ds_read_b128 v[210:213], v152 offset:5120
	ds_read_b128 v[214:217], v152 offset:6144
	ds_read_b128 v[218:221], v152 offset:7168
	global_load_lds_dwordx4 v136, s[20:21]
	s_add_i32 m0, s35, 0xe000
	s_nop 0
	global_load_lds_dwordx4 v138, s[20:21]
	s_waitcnt vmcnt(8)
	s_waitcnt lgkmcnt(0)
	s_barrier
	v_mfma_f32_16x16x32_bf16 v[124:127], v[154:157], v[186:189], v[124:127]
	v_mfma_f32_16x16x32_bf16 v[116:119], v[162:165], v[186:189], v[116:119]
	v_mfma_f32_16x16x32_bf16 v[108:111], v[154:157], v[198:201], v[108:111]
	v_mfma_f32_16x16x32_bf16 v[100:103], v[162:165], v[198:201], v[100:103]
	v_mfma_f32_16x16x32_bf16 v[92:95], v[154:157], v[206:209], v[92:95]
	v_mfma_f32_16x16x32_bf16 v[84:87], v[162:165], v[206:209], v[84:87]
	v_mfma_f32_16x16x32_bf16 v[76:79], v[154:157], v[214:217], v[76:79]
	v_mfma_f32_16x16x32_bf16 v[68:71], v[162:165], v[214:217], v[68:71]
	v_mfma_f32_16x16x32_bf16 v[124:127], v[158:161], v[190:193], v[124:127]
	v_mfma_f32_16x16x32_bf16 v[116:119], v[166:169], v[190:193], v[116:119]
	v_mfma_f32_16x16x32_bf16 v[108:111], v[158:161], v[202:205], v[108:111]
	v_mfma_f32_16x16x32_bf16 v[100:103], v[166:169], v[202:205], v[100:103]
	v_mfma_f32_16x16x32_bf16 v[92:95], v[158:161], v[210:213], v[92:95]
	v_mfma_f32_16x16x32_bf16 v[84:87], v[166:169], v[210:213], v[84:87]
	v_mfma_f32_16x16x32_bf16 v[76:79], v[158:161], v[218:221], v[76:79]
	v_mfma_f32_16x16x32_bf16 v[68:71], v[166:169], v[218:221], v[68:71]
	v_mfma_f32_16x16x32_bf16 v[120:123], v[170:173], v[186:189], v[120:123]
	v_mfma_f32_16x16x32_bf16 v[112:115], v[178:181], v[186:189], v[112:115]
	v_mfma_f32_16x16x32_bf16 v[104:107], v[170:173], v[198:201], v[104:107]
	v_mfma_f32_16x16x32_bf16 v[96:99], v[178:181], v[198:201], v[96:99]
	v_mfma_f32_16x16x32_bf16 v[88:91], v[170:173], v[206:209], v[88:91]
	v_mfma_f32_16x16x32_bf16 v[80:83], v[178:181], v[206:209], v[80:83]
	v_mfma_f32_16x16x32_bf16 v[72:75], v[170:173], v[214:217], v[72:75]
	v_mfma_f32_16x16x32_bf16 v[64:67], v[178:181], v[214:217], v[64:67]
	v_mfma_f32_16x16x32_bf16 v[120:123], v[174:177], v[190:193], v[120:123]
	v_mfma_f32_16x16x32_bf16 v[112:115], v[182:185], v[190:193], v[112:115]
	v_mfma_f32_16x16x32_bf16 v[104:107], v[174:177], v[202:205], v[104:107]
	v_mfma_f32_16x16x32_bf16 v[96:99], v[182:185], v[202:205], v[96:99]
	v_mfma_f32_16x16x32_bf16 v[88:91], v[174:177], v[210:213], v[88:91]
	v_mfma_f32_16x16x32_bf16 v[80:83], v[182:185], v[210:213], v[80:83]
	v_mfma_f32_16x16x32_bf16 v[72:75], v[174:177], v[218:221], v[72:75]
	v_mfma_f32_16x16x32_bf16 v[64:67], v[182:185], v[218:221], v[64:67]
	s_barrier
	s_add_i32 s68, s58, s50
	s_add_u32 s98, s38, s8
	s_addc_u32 s99, s39, s9
	s_add_u32 s100, s42, s8
	s_addc_u32 s101, s43, s9
	s_mov_b32 m0, s68
	ds_read_b128 v[186:189], v152 offset:16384
	ds_read_b128 v[190:193], v152 offset:17408
	ds_read_b128 v[198:201], v152 offset:18432
	ds_read_b128 v[202:205], v152 offset:19456
	ds_read_b128 v[206:209], v152 offset:20480
	ds_read_b128 v[210:213], v152 offset:21504
	ds_read_b128 v[214:217], v152 offset:22528
	ds_read_b128 v[218:221], v152 offset:23552
	global_load_lds_dwordx4 v132, s[38:39]
	s_add_i32 m0, s68, 0x2000
	s_add_u32 s68, s38, 0x40000
	s_addc_u32 s69, s39, 0
	s_add_i32 s70, s59, s50
	global_load_lds_dwordx4 v128, s[38:39]
	s_mov_b32 m0, s70
	s_nop 0
	global_load_lds_dwordx4 v132, s[68:69]
	s_add_i32 m0, s70, 0x2000
	s_nop 0
	global_load_lds_dwordx4 v128, s[68:69]
	s_mov_b32 m0, s35
	s_nop 0
	global_load_lds_dwordx4 v134, s[42:43]
	s_mov_b32 m0, s52
	s_nop 0
	global_load_lds_dwordx4 v130, s[42:43]
	s_waitcnt vmcnt(8)
	s_waitcnt lgkmcnt(0)
	s_barrier
	v_mfma_f32_16x16x32_bf16 v[60:63], v[154:157], v[186:189], v[60:63]
	v_mfma_f32_16x16x32_bf16 v[52:55], v[162:165], v[186:189], v[52:55]
	v_mfma_f32_16x16x32_bf16 v[44:47], v[154:157], v[198:201], v[44:47]
	v_mfma_f32_16x16x32_bf16 v[36:39], v[162:165], v[198:201], v[36:39]
	v_mfma_f32_16x16x32_bf16 v[28:31], v[154:157], v[206:209], v[28:31]
	v_mfma_f32_16x16x32_bf16 v[20:23], v[162:165], v[206:209], v[20:23]
	v_mfma_f32_16x16x32_bf16 v[12:15], v[154:157], v[214:217], v[12:15]
	v_mfma_f32_16x16x32_bf16 v[4:7], v[162:165], v[214:217], v[4:7]
	v_mfma_f32_16x16x32_bf16 v[60:63], v[158:161], v[190:193], v[60:63]
	v_mfma_f32_16x16x32_bf16 v[52:55], v[166:169], v[190:193], v[52:55]
	v_mfma_f32_16x16x32_bf16 v[44:47], v[158:161], v[202:205], v[44:47]
	v_mfma_f32_16x16x32_bf16 v[36:39], v[166:169], v[202:205], v[36:39]
	v_mfma_f32_16x16x32_bf16 v[28:31], v[158:161], v[210:213], v[28:31]
	v_mfma_f32_16x16x32_bf16 v[20:23], v[166:169], v[210:213], v[20:23]
	v_mfma_f32_16x16x32_bf16 v[12:15], v[158:161], v[218:221], v[12:15]
	v_mfma_f32_16x16x32_bf16 v[4:7], v[166:169], v[218:221], v[4:7]
	v_mfma_f32_16x16x32_bf16 v[56:59], v[170:173], v[186:189], v[56:59]
	v_mfma_f32_16x16x32_bf16 v[48:51], v[178:181], v[186:189], v[48:51]
	v_mfma_f32_16x16x32_bf16 v[40:43], v[170:173], v[198:201], v[40:43]
	v_mfma_f32_16x16x32_bf16 v[32:35], v[178:181], v[198:201], v[32:35]
	v_mfma_f32_16x16x32_bf16 v[24:27], v[170:173], v[206:209], v[24:27]
	v_mfma_f32_16x16x32_bf16 v[16:19], v[178:181], v[206:209], v[16:19]
	v_mfma_f32_16x16x32_bf16 v[8:11], v[170:173], v[214:217], v[8:11]
	v_mfma_f32_16x16x32_bf16 v[0:3], v[178:181], v[214:217], v[0:3]
	v_mfma_f32_16x16x32_bf16 v[56:59], v[174:177], v[190:193], v[56:59]
	v_mfma_f32_16x16x32_bf16 v[48:51], v[182:185], v[190:193], v[48:51]
	v_mfma_f32_16x16x32_bf16 v[40:43], v[174:177], v[202:205], v[40:43]
	v_mfma_f32_16x16x32_bf16 v[32:35], v[182:185], v[202:205], v[32:35]
	v_mfma_f32_16x16x32_bf16 v[24:27], v[174:177], v[210:213], v[24:27]
	v_mfma_f32_16x16x32_bf16 v[16:19], v[182:185], v[210:213], v[16:19]
	v_mfma_f32_16x16x32_bf16 v[8:11], v[174:177], v[218:221], v[8:11]
	v_mfma_f32_16x16x32_bf16 v[0:3], v[182:185], v[218:221], v[0:3]
	s_barrier
; #define PG8_STAGE(bufoff, gbase, voff) do { _Pragma("unroll") for (int _i = 0; _i < 2; ++_i) \
;         __builtin_amdgcn_global_load_lds((const unsigned*)((const char*)(gbase) + (voff)[_i]), (PG8_LAS unsigned*)(lds + (bufoff) + ldsw + _i * 8192), 16, 0, 0); } while (0)
; #define PG8_LDA(dst, b, h) do { _Pragma("unroll") for (int m = 0; m < 4; ++m) _Pragma("unroll") for (int k = 0; k < 2; ++k) dst[m][k] = *(const PG8_LAS bf16x8*)(lds + PG8_SA(b, h) + aoff + m * 2048 + k * 1024); } while (0)
; #define PG8_LDB(dst, b, h) do { _Pragma("unroll") for (int n = 0; n < 2; ++n) _Pragma("unroll") for (int k = 0; k < 2; ++k) dst[n][k] = *(const PG8_LAS bf16x8*)(lds + PG8_SB(b, h) + boff + n * 2048 + k * 1024); } while (0)
; #define PG8_MMA(ai, bj, At, Bt) do { __builtin_amdgcn_s_setprio(1); _Pragma("unroll") for (int m = 0; m < 4; ++m) _Pragma("unroll") for (int n = 0; n < 2; ++n) _Pragma("unroll") for (int k = 0; k < 2; ++k) \
;         acc[ai][bj][m][n] = __builtin_amdgcn_mfma_f32_16x16x32_bf16(Bt[n][k], At[m][k], acc[ai][bj][m][n], 0, 0, 0); __builtin_amdgcn_s_setprio(0); } while (0)
; #define PG8_WAIT_V(n) asm volatile("s_waitcnt vmcnt(" #n ")" ::: "memory")
; #define PG8_WAIT_L(n) asm volatile("s_waitcnt lgkmcnt(" #n ")" ::: "memory")
; #define PG8_BAR __builtin_amdgcn_s_barrier()
; #define PG8_SCHED __builtin_amdgcn_sched_barrier(0)
; template <class Epi, class Sched, bool ALIGN_EPI = false, bool SP2 = false>
; __device__ __forceinline__ void gemm_phase(PG8_LAS unsigned char* lds, const Gemm g, const Sched& S, const Epi& E) {
;     ...
;             PG8_LDB(B0, 1, 0); PG8_LDB(B1, 1, 1); PG8_SCHED; PG8_LDA(At, 1, 0); PG8_STAGE(PG8_SA(0, 1), a2 + hstep, voffA);
;             PG8_WAIT_V(8); PG8_WAIT_L(0); PG8_BAR; PG8_MMA(0, 0, At, B0); PG8_MMA(0, 1, At, B1); PG8_BAR; PG8_SCHED;
;             PG8_LDA(At, 1, 1); PG8_STAGE(PG8_SB(1, 0), b3, voffB); PG8_STAGE(PG8_SB(1, 1), b3 + hstep, voffB); PG8_STAGE(PG8_SA(1, 0), a3, voffA);
;             PG8_WAIT_V(8); PG8_WAIT_L(0); PG8_BAR; PG8_MMA(1, 0, At, B0); PG8_MMA(1, 1, At, B1); PG8_BAR; PG8_SCHED;
	s_add_i32 s68, 0, 0x18000
	v_add_u32_e32 v153, s68, v147
	s_add_i32 s69, 0, 0x1c000
	ds_read_b128 v[154:157], v153
	ds_read_b128 v[158:161], v153 offset:1024
	ds_read_b128 v[162:165], v153 offset:2048
	ds_read_b128 v[166:169], v153 offset:3072
	v_add_u32_e32 v153, s69, v147
	ds_read_b128 v[170:173], v153
	ds_read_b128 v[174:177], v153 offset:1024
	ds_read_b128 v[178:181], v153 offset:2048
	ds_read_b128 v[182:185], v153 offset:3072
	s_add_u32 s42, s42, 0x40000
	s_addc_u32 s43, s43, 0
	s_mov_b32 m0, s53
	ds_read_b128 v[186:189], v152 offset:32768
	ds_read_b128 v[190:193], v152 offset:33792
	ds_read_b128 v[198:201], v152 offset:34816
	ds_read_b128 v[202:205], v152 offset:35840
	ds_read_b128 v[206:209], v152 offset:36864
	ds_read_b128 v[210:213], v152 offset:37888
	ds_read_b128 v[214:217], v152 offset:38912
	ds_read_b128 v[218:221], v152 offset:39936
	global_load_lds_dwordx4 v134, s[42:43]
	s_mov_b32 m0, s54
	s_nop 0
	global_load_lds_dwordx4 v130, s[42:43]
	s_waitcnt vmcnt(8)
	s_waitcnt lgkmcnt(0)
	s_barrier
	v_mfma_f32_16x16x32_bf16 v[124:127], v[154:157], v[186:189], v[124:127]
	v_mfma_f32_16x16x32_bf16 v[116:119], v[162:165], v[186:189], v[116:119]
	v_mfma_f32_16x16x32_bf16 v[108:111], v[154:157], v[198:201], v[108:111]
	v_mfma_f32_16x16x32_bf16 v[100:103], v[162:165], v[198:201], v[100:103]
	v_mfma_f32_16x16x32_bf16 v[92:95], v[154:157], v[206:209], v[92:95]
	v_mfma_f32_16x16x32_bf16 v[84:87], v[162:165], v[206:209], v[84:87]
	v_mfma_f32_16x16x32_bf16 v[76:79], v[154:157], v[214:217], v[76:79]
	v_mfma_f32_16x16x32_bf16 v[68:71], v[162:165], v[214:217], v[68:71]
	v_mfma_f32_16x16x32_bf16 v[124:127], v[158:161], v[190:193], v[124:127]
	v_mfma_f32_16x16x32_bf16 v[116:119], v[166:169], v[190:193], v[116:119]
	v_mfma_f32_16x16x32_bf16 v[108:111], v[158:161], v[202:205], v[108:111]
	v_mfma_f32_16x16x32_bf16 v[100:103], v[166:169], v[202:205], v[100:103]
	v_mfma_f32_16x16x32_bf16 v[92:95], v[158:161], v[210:213], v[92:95]
	v_mfma_f32_16x16x32_bf16 v[84:87], v[166:169], v[210:213], v[84:87]
	v_mfma_f32_16x16x32_bf16 v[76:79], v[158:161], v[218:221], v[76:79]
	v_mfma_f32_16x16x32_bf16 v[68:71], v[166:169], v[218:221], v[68:71]
	v_mfma_f32_16x16x32_bf16 v[120:123], v[170:173], v[186:189], v[120:123]
	v_mfma_f32_16x16x32_bf16 v[112:115], v[178:181], v[186:189], v[112:115]
	v_mfma_f32_16x16x32_bf16 v[104:107], v[170:173], v[198:201], v[104:107]
	v_mfma_f32_16x16x32_bf16 v[96:99], v[178:181], v[198:201], v[96:99]
	v_mfma_f32_16x16x32_bf16 v[88:91], v[170:173], v[206:209], v[88:91]
	v_mfma_f32_16x16x32_bf16 v[80:83], v[178:181], v[206:209], v[80:83]
	v_mfma_f32_16x16x32_bf16 v[72:75], v[170:173], v[214:217], v[72:75]
	v_mfma_f32_16x16x32_bf16 v[64:67], v[178:181], v[214:217], v[64:67]
	v_mfma_f32_16x16x32_bf16 v[120:123], v[174:177], v[190:193], v[120:123]
	v_mfma_f32_16x16x32_bf16 v[112:115], v[182:185], v[190:193], v[112:115]
	v_mfma_f32_16x16x32_bf16 v[104:107], v[174:177], v[202:205], v[104:107]
	v_mfma_f32_16x16x32_bf16 v[96:99], v[182:185], v[202:205], v[96:99]
	v_mfma_f32_16x16x32_bf16 v[88:91], v[174:177], v[210:213], v[88:91]
	v_mfma_f32_16x16x32_bf16 v[80:83], v[182:185], v[210:213], v[80:83]
	v_mfma_f32_16x16x32_bf16 v[72:75], v[174:177], v[218:221], v[72:75]
	v_mfma_f32_16x16x32_bf16 v[64:67], v[182:185], v[218:221], v[64:67]
	s_barrier
	s_add_i32 s42, s68, s50
	s_mov_b32 m0, s42
	ds_read_b128 v[186:189], v152 offset:49152
	ds_read_b128 v[190:193], v152 offset:50176
	ds_read_b128 v[198:201], v152 offset:51200
	ds_read_b128 v[202:205], v152 offset:52224
	ds_read_b128 v[206:209], v152 offset:53248
	ds_read_b128 v[210:213], v152 offset:54272
	ds_read_b128 v[214:217], v152 offset:55296
	ds_read_b128 v[218:221], v152 offset:56320
	global_load_lds_dwordx4 v132, s[98:99]
	s_add_i32 m0, s42, 0x2000
	s_add_u32 s38, s38, 0x40080
	s_addc_u32 s39, s39, 0
	s_add_i32 s42, s69, s50
	global_load_lds_dwordx4 v128, s[98:99]
	s_mov_b32 m0, s42
	s_nop 0
	global_load_lds_dwordx4 v132, s[38:39]
	s_add_i32 m0, s42, 0x2000
	s_nop 0
	global_load_lds_dwordx4 v128, s[38:39]
	s_mov_b32 m0, s56
	s_nop 0
	global_load_lds_dwordx4 v134, s[100:101]
	s_mov_b32 m0, s57
	s_nop 0
	global_load_lds_dwordx4 v130, s[100:101]
	s_waitcnt vmcnt(8)
	s_waitcnt lgkmcnt(0)
	s_barrier
	v_mfma_f32_16x16x32_bf16 v[60:63], v[154:157], v[186:189], v[60:63]
	v_mfma_f32_16x16x32_bf16 v[52:55], v[162:165], v[186:189], v[52:55]
	v_mfma_f32_16x16x32_bf16 v[44:47], v[154:157], v[198:201], v[44:47]
	v_mfma_f32_16x16x32_bf16 v[36:39], v[162:165], v[198:201], v[36:39]
	v_mfma_f32_16x16x32_bf16 v[28:31], v[154:157], v[206:209], v[28:31]
	v_mfma_f32_16x16x32_bf16 v[20:23], v[162:165], v[206:209], v[20:23]
	v_mfma_f32_16x16x32_bf16 v[12:15], v[154:157], v[214:217], v[12:15]
	v_mfma_f32_16x16x32_bf16 v[4:7], v[162:165], v[214:217], v[4:7]
	v_mfma_f32_16x16x32_bf16 v[60:63], v[158:161], v[190:193], v[60:63]
	v_mfma_f32_16x16x32_bf16 v[52:55], v[166:169], v[190:193], v[52:55]
	v_mfma_f32_16x16x32_bf16 v[44:47], v[158:161], v[202:205], v[44:47]
	v_mfma_f32_16x16x32_bf16 v[36:39], v[166:169], v[202:205], v[36:39]
	v_mfma_f32_16x16x32_bf16 v[28:31], v[158:161], v[210:213], v[28:31]
	v_mfma_f32_16x16x32_bf16 v[20:23], v[166:169], v[210:213], v[20:23]
	v_mfma_f32_16x16x32_bf16 v[12:15], v[158:161], v[218:221], v[12:15]
	v_mfma_f32_16x16x32_bf16 v[4:7], v[166:169], v[218:221], v[4:7]
	v_mfma_f32_16x16x32_bf16 v[56:59], v[170:173], v[186:189], v[56:59]
	v_mfma_f32_16x16x32_bf16 v[48:51], v[178:181], v[186:189], v[48:51]
	v_mfma_f32_16x16x32_bf16 v[40:43], v[170:173], v[198:201], v[40:43]
	v_mfma_f32_16x16x32_bf16 v[32:35], v[178:181], v[198:201], v[32:35]
	v_mfma_f32_16x16x32_bf16 v[24:27], v[170:173], v[206:209], v[24:27]
	v_mfma_f32_16x16x32_bf16 v[16:19], v[178:181], v[206:209], v[16:19]
	v_mfma_f32_16x16x32_bf16 v[8:11], v[170:173], v[214:217], v[8:11]
	v_mfma_f32_16x16x32_bf16 v[0:3], v[178:181], v[214:217], v[0:3]
	v_mfma_f32_16x16x32_bf16 v[56:59], v[174:177], v[190:193], v[56:59]
	v_mfma_f32_16x16x32_bf16 v[48:51], v[182:185], v[190:193], v[48:51]
	v_mfma_f32_16x16x32_bf16 v[40:43], v[174:177], v[202:205], v[40:43]
	v_mfma_f32_16x16x32_bf16 v[32:35], v[182:185], v[202:205], v[32:35]
	v_mfma_f32_16x16x32_bf16 v[24:27], v[174:177], v[210:213], v[24:27]
	v_mfma_f32_16x16x32_bf16 v[16:19], v[182:185], v[210:213], v[16:19]
	v_mfma_f32_16x16x32_bf16 v[8:11], v[174:177], v[218:221], v[8:11]
	v_mfma_f32_16x16x32_bf16 v[0:3], v[182:185], v[218:221], v[0:3]
	s_barrier
	s_add_i32 s67, s67, 2
	s_add_u32 s20, s20, 0x100
	s_addc_u32 s21, s21, 0
	s_add_u32 s65, s65, 0x100
	s_addc_u32 s66, s66, 0
	s_cmp_gt_u32 s67, 13
	s_cbranch_scc0 .LBB0_1740
	v_readlane_b32 s101, v249, 49
	s_nop 3
	s_cmp_eq_u32 s101, 0
	s_cbranch_scc1 .Ldw_done_3
	s_add_u32 s98, s28, 0x183500
	s_addc_u32 s99, s29, 0
	v_mov_b32_e32 v251, 0
	s_mov_b32 s100, 0

; __global__ void __launch_bounds__(NTHREADS, 2) mega_fwd(Args a) {
	.amdhsa_kernel _Z8mega_fwd4Args
		.amdhsa_group_segment_fixed_size 0
		.amdhsa_private_segment_fixed_size 0
		.amdhsa_kernarg_size 480
		.amdhsa_user_sgpr_count 2
		.amdhsa_user_sgpr_dispatch_ptr 0
		.amdhsa_user_sgpr_queue_ptr 0
		.amdhsa_user_sgpr_kernarg_segment_ptr 1
		.amdhsa_user_sgpr_dispatch_id 0
		.amdhsa_user_sgpr_kernarg_preload_length 0
		.amdhsa_user_sgpr_kernarg_preload_offset 0
		.amdhsa_user_sgpr_private_segment_size 0
		.amdhsa_uses_dynamic_stack 0
		.amdhsa_enable_private_segment 0
		.amdhsa_system_sgpr_workgroup_id_x 1
		.amdhsa_system_sgpr_workgroup_id_y 0
		.amdhsa_system_sgpr_workgroup_id_z 0
		.amdhsa_system_sgpr_workgroup_info 0
		.amdhsa_system_vgpr_workitem_id 2
		.amdhsa_next_free_vgpr 252
		.amdhsa_next_free_sgpr 102
		.amdhsa_accum_offset 252
		.amdhsa_reserve_vcc 1
		.amdhsa_float_round_mode_32 0
		.amdhsa_float_round_mode_16_64 0
		.amdhsa_float_denorm_mode_32 3
		.amdhsa_float_denorm_mode_16_64 3
		.amdhsa_dx10_clamp 1
		.amdhsa_ieee_mode 1
		.amdhsa_fp16_overflow 0
		.amdhsa_tg_split 0
		.amdhsa_exception_fp_ieee_invalid_op 0
		.amdhsa_exception_fp_denorm_src 0
		.amdhsa_exception_fp_ieee_div_zero 0
		.amdhsa_exception_fp_ieee_overflow 0
		.amdhsa_exception_fp_ieee_underflow 0
		.amdhsa_exception_fp_ieee_inexact 0
		.amdhsa_exception_int_div_zero 0
	.end_amdhsa_kernel

; __global__ void __launch_bounds__(NTHREADS, 2) mega_fwd(Args a) {
amdhsa.kernels:
  - .agpr_count:     0
    .args:
      - .offset:         0
        .size:           224
        .value_kind:     by_value
      - .offset:         224
        .size:           4
        .value_kind:     hidden_block_count_x
      - .offset:         228
        .size:           4
        .value_kind:     hidden_block_count_y
      - .offset:         232
        .size:           4
        .value_kind:     hidden_block_count_z
      - .offset:         236
        .size:           2
        .value_kind:     hidden_group_size_x
      - .offset:         238
        .size:           2
        .value_kind:     hidden_group_size_y
      - .offset:         240
        .size:           2
        .value_kind:     hidden_group_size_z
      - .offset:         242
        .size:           2
        .value_kind:     hidden_remainder_x
      - .offset:         244
        .size:           2
        .value_kind:     hidden_remainder_y
      - .offset:         246
        .size:           2
        .value_kind:     hidden_remainder_z
      - .offset:         264
        .size:           8
        .value_kind:     hidden_global_offset_x
      - .offset:         272
        .size:           8
        .value_kind:     hidden_global_offset_y
      - .offset:         280
        .size:           8
        .value_kind:     hidden_global_offset_z
      - .offset:         288
        .size:           2
        .value_kind:     hidden_grid_dims
      - .offset:         312
        .size:           8
        .value_kind:     hidden_multigrid_sync_arg
      - .offset:         344
        .size:           4
        .value_kind:     hidden_dynamic_lds_size
    .group_segment_fixed_size: 0
    .kernarg_segment_align: 8
    .kernarg_segment_size: 480
    .language:       OpenCL C
    .language_version:
      - 2
      - 0
    .max_flat_workgroup_size: 512
    .name:           _Z8mega_fwd4Args
    .private_segment_fixed_size: 0
    .sgpr_count:     108
    .sgpr_spill_count: 40
    .symbol:         _Z8mega_fwd4Args.kd
    .uniform_work_group_size: 1
    .uses_dynamic_stack: false
    .vgpr_count:     252
    .vgpr_spill_count: 0
    .wavefront_size: 64
